# peeled first K iteration per tile: first MFMA of each accumulator takes SrcC=0, 128 zero-init v_mov per tile removed (8 prompt GEMM loops)
# speedup vs baseline: 1.0071x; 1.0008x over previous
.LBB0_271:
	s_add_i32 s35, s35, 1
	s_mov_b32 s49, s6
	s_lshl_b32 s6, s35, 5
	s_add_i32 s6, s6, s3
	s_mov_b64 s[24:25], s[8:9]
	s_lshl_b32 s8, s6, 3
	s_ashr_i32 s7, s6, 2
	s_add_i32 s8, s8, s38
	s_cmpk_lt_i32 s6, 0x104
	s_cselect_b32 s6, s7, s8
	s_mov_b32 s50, s28
	s_cselect_b32 s28, s39, 32
	s_cmpk_lt_i32 s6, 0x41
	s_cselect_b64 s[20:21], -1, 0
	s_lshl_b32 s7, s28, 21
	v_readlane_b32 s0, v250, 46
	s_mov_b64 s[22:23], s[10:11]
	v_readlane_b32 s1, v250, 47
	s_add_u32 s10, s0, s7
	s_addc_u32 s11, s1, 0
	s_and_b64 s[8:9], s[20:21], exec
	s_cselect_b32 s51, s11, s23
	s_cselect_b32 s52, s10, s22
	s_ashr_i32 s7, s6, 31
	s_lshl_b64 s[8:9], s[6:7], 21
	v_readlane_b32 s0, v250, 38
	v_readlane_b32 s1, v250, 39
	s_add_u32 s8, s0, s8
	s_addc_u32 s9, s1, s9
	s_and_b64 s[26:27], s[20:21], exec
	s_cselect_b32 s7, s9, s25
	s_cselect_b32 s53, s8, s24
	s_add_u32 s22, s22, 0x100080
	s_addc_u32 s23, s23, 0
	s_add_u32 s54, s24, 0x100
	s_addc_u32 s55, s25, 0
	s_mov_b32 s56, -2
	s_add_u32 s58, s22, 0xfff00000
	s_addc_u32 s59, s23, -1
	s_mov_b32 m0, s36
	ds_read_b128 v[154:157], v148
	global_load_lds_dwordx4 v130, s[58:59]
	s_mov_b32 m0, s37
	ds_read_b128 v[158:161], v148 offset:1024
	global_load_lds_dwordx4 v134, s[58:59]
	s_mov_b32 m0, s40
	ds_read_b128 v[164:167], v148 offset:2048
	global_load_lds_dwordx4 v142, s[22:23]
	s_mov_b32 m0, s41
	ds_read_b128 v[168:171], v148 offset:3072
	global_load_lds_dwordx4 v144, s[22:23]
	ds_read_b128 v[172:175], v149
	ds_read_b128 v[176:179], v149 offset:1024
	ds_read_b128 v[180:183], v149 offset:2048
	ds_read_b128 v[184:187], v149 offset:3072
	s_add_u32 s24, s22, 0xfff00080
	s_addc_u32 s25, s23, -1
	s_cmp_eq_u32 s56, 60
	s_cselect_b32 s27, s51, s25
	s_cselect_b32 s26, s52, s24
	s_cselect_b32 s25, s7, s55
	s_cselect_b32 s24, s53, s54
	ds_read_b128 v[188:191], v150
	ds_read_b128 v[192:195], v150 offset:1024
	ds_read_b128 v[196:199], v150 offset:2048
	ds_read_b128 v[200:203], v150 offset:3072
	ds_read_b128 v[204:207], v150 offset:4096
	ds_read_b128 v[208:211], v150 offset:5120
	ds_read_b128 v[212:215], v150 offset:6144
	ds_read_b128 v[216:219], v150 offset:7168
	s_waitcnt vmcnt(8)
	s_waitcnt lgkmcnt(0)
	s_barrier
	v_mfma_f32_16x16x32_bf16 v[126:129], v[154:157], v[188:191], 0
	v_mfma_f32_16x16x32_bf16 v[126:129], v[158:161], v[192:195], v[126:129]
	v_mfma_f32_16x16x32_bf16 v[122:125], v[168:171], v[192:195], 0
	v_mfma_f32_16x16x32_bf16 v[122:125], v[164:167], v[188:191], v[122:125]
	v_mfma_f32_16x16x32_bf16 v[114:117], v[164:167], v[196:199], 0
	v_mfma_f32_16x16x32_bf16 v[114:117], v[168:171], v[200:203], v[114:117]
	v_mfma_f32_16x16x32_bf16 v[118:121], v[158:161], v[200:203], 0
	v_mfma_f32_16x16x32_bf16 v[118:121], v[154:157], v[196:199], v[118:121]
	v_mfma_f32_16x16x32_bf16 v[102:105], v[154:157], v[204:207], 0
	v_mfma_f32_16x16x32_bf16 v[102:105], v[158:161], v[208:211], v[102:105]
	v_mfma_f32_16x16x32_bf16 v[98:101], v[168:171], v[208:211], 0
	v_mfma_f32_16x16x32_bf16 v[98:101], v[164:167], v[204:207], v[98:101]
	v_mfma_f32_16x16x32_bf16 v[82:85], v[164:167], v[212:215], 0
	v_mfma_f32_16x16x32_bf16 v[82:85], v[168:171], v[216:219], v[82:85]
	v_mfma_f32_16x16x32_bf16 v[86:89], v[158:161], v[216:219], 0
	v_mfma_f32_16x16x32_bf16 v[86:89], v[154:157], v[212:215], v[86:89]
	v_mfma_f32_16x16x32_bf16 v[70:73], v[172:175], v[212:215], 0
	v_mfma_f32_16x16x32_bf16 v[70:73], v[176:179], v[216:219], v[70:73]
	v_mfma_f32_16x16x32_bf16 v[66:69], v[184:187], v[216:219], 0
	v_mfma_f32_16x16x32_bf16 v[66:69], v[180:183], v[212:215], v[66:69]
	v_mfma_f32_16x16x32_bf16 v[74:77], v[180:183], v[204:207], 0
	v_mfma_f32_16x16x32_bf16 v[74:77], v[184:187], v[208:211], v[74:77]
	v_mfma_f32_16x16x32_bf16 v[78:81], v[176:179], v[208:211], 0
	v_mfma_f32_16x16x32_bf16 v[78:81], v[172:175], v[204:207], v[78:81]
	v_mfma_f32_16x16x32_bf16 v[94:97], v[172:175], v[196:199], 0
	v_mfma_f32_16x16x32_bf16 v[94:97], v[176:179], v[200:203], v[94:97]
	v_mfma_f32_16x16x32_bf16 v[90:93], v[184:187], v[200:203], 0
	v_mfma_f32_16x16x32_bf16 v[90:93], v[180:183], v[196:199], v[90:93]
	v_mfma_f32_16x16x32_bf16 v[106:109], v[180:183], v[188:191], 0
	v_mfma_f32_16x16x32_bf16 v[106:109], v[184:187], v[192:195], v[106:109]
	v_mfma_f32_16x16x32_bf16 v[110:113], v[176:179], v[192:195], 0
	v_mfma_f32_16x16x32_bf16 v[110:113], v[172:175], v[188:191], v[110:113]
	s_barrier
	s_mov_b32 m0, s42
	s_add_u32 s58, s24, 0x100000
	global_load_lds_dwordx4 v132, s[24:25]
	s_mov_b32 m0, s43
	s_addc_u32 s59, s25, 0
	global_load_lds_dwordx4 v136, s[24:25]
	s_mov_b32 m0, s44
	ds_read_b128 v[188:191], v150 offset:16384
	global_load_lds_dwordx4 v132, s[58:59]
	s_mov_b32 m0, s45
	ds_read_b128 v[192:195], v150 offset:17408
	global_load_lds_dwordx4 v136, s[58:59]
	ds_read_b128 v[196:199], v150 offset:18432
	ds_read_b128 v[200:203], v150 offset:19456
	ds_read_b128 v[204:207], v150 offset:20480
	ds_read_b128 v[208:211], v150 offset:21504
	ds_read_b128 v[212:215], v150 offset:22528
	ds_read_b128 v[216:219], v150 offset:23552
	s_waitcnt vmcnt(6)
	s_waitcnt lgkmcnt(0)
	s_barrier
	v_mfma_f32_16x16x32_bf16 v[62:65], v[154:157], v[188:191], 0
	v_mfma_f32_16x16x32_bf16 v[62:65], v[158:161], v[192:195], v[62:65]
	v_mfma_f32_16x16x32_bf16 v[58:61], v[168:171], v[192:195], 0
	v_mfma_f32_16x16x32_bf16 v[58:61], v[164:167], v[188:191], v[58:61]
	v_mfma_f32_16x16x32_bf16 v[50:53], v[164:167], v[196:199], 0
	v_mfma_f32_16x16x32_bf16 v[50:53], v[168:171], v[200:203], v[50:53]
	v_mfma_f32_16x16x32_bf16 v[54:57], v[158:161], v[200:203], 0
	v_mfma_f32_16x16x32_bf16 v[54:57], v[154:157], v[196:199], v[54:57]
	v_mfma_f32_16x16x32_bf16 v[38:41], v[154:157], v[204:207], 0
	v_mfma_f32_16x16x32_bf16 v[38:41], v[158:161], v[208:211], v[38:41]
	v_mfma_f32_16x16x32_bf16 v[34:37], v[168:171], v[208:211], 0
	v_mfma_f32_16x16x32_bf16 v[34:37], v[164:167], v[204:207], v[34:37]
	v_mfma_f32_16x16x32_bf16 v[18:21], v[164:167], v[212:215], 0
	v_mfma_f32_16x16x32_bf16 v[18:21], v[168:171], v[216:219], v[18:21]
	v_mfma_f32_16x16x32_bf16 v[22:25], v[158:161], v[216:219], 0
	v_mfma_f32_16x16x32_bf16 v[22:25], v[154:157], v[212:215], v[22:25]
	v_mfma_f32_16x16x32_bf16 v[6:9], v[172:175], v[212:215], 0
	v_mfma_f32_16x16x32_bf16 v[6:9], v[176:179], v[216:219], v[6:9]
	v_mfma_f32_16x16x32_bf16 v[2:5], v[184:187], v[216:219], 0
	v_mfma_f32_16x16x32_bf16 v[2:5], v[180:183], v[212:215], v[2:5]
	v_mfma_f32_16x16x32_bf16 v[10:13], v[180:183], v[204:207], 0
	v_mfma_f32_16x16x32_bf16 v[10:13], v[184:187], v[208:211], v[10:13]
	v_mfma_f32_16x16x32_bf16 v[14:17], v[176:179], v[208:211], 0
	v_mfma_f32_16x16x32_bf16 v[14:17], v[172:175], v[204:207], v[14:17]
	v_mfma_f32_16x16x32_bf16 v[30:33], v[172:175], v[196:199], 0
	v_mfma_f32_16x16x32_bf16 v[30:33], v[176:179], v[200:203], v[30:33]
	v_mfma_f32_16x16x32_bf16 v[26:29], v[184:187], v[200:203], 0
	v_mfma_f32_16x16x32_bf16 v[26:29], v[180:183], v[196:199], v[26:29]
	v_mfma_f32_16x16x32_bf16 v[42:45], v[180:183], v[188:191], 0
	v_mfma_f32_16x16x32_bf16 v[42:45], v[184:187], v[192:195], v[42:45]
	v_mfma_f32_16x16x32_bf16 v[46:49], v[176:179], v[192:195], 0
	v_mfma_f32_16x16x32_bf16 v[46:49], v[172:175], v[188:191], v[46:49]
	s_barrier
	s_mov_b32 m0, s30
	ds_read_b128 v[154:157], v151
	global_load_lds_dwordx4 v130, s[26:27]
	s_mov_b32 m0, s31
	ds_read_b128 v[158:161], v151 offset:1024
	global_load_lds_dwordx4 v134, s[26:27]
	s_add_u32 s26, s26, 0x100000
	s_addc_u32 s27, s27, 0
	s_mov_b32 m0, s33
	ds_read_b128 v[164:167], v151 offset:2048
	global_load_lds_dwordx4 v130, s[26:27]
	s_mov_b32 m0, s34
	ds_read_b128 v[168:171], v151 offset:3072
	global_load_lds_dwordx4 v134, s[26:27]
	ds_read_b128 v[172:175], v152
	ds_read_b128 v[176:179], v152 offset:1024
	ds_read_b128 v[180:183], v152 offset:2048
	ds_read_b128 v[184:187], v152 offset:3072
	ds_read_b128 v[188:191], v150 offset:32768
	ds_read_b128 v[192:195], v150 offset:33792
	ds_read_b128 v[196:199], v150 offset:34816
	ds_read_b128 v[200:203], v150 offset:35840
	ds_read_b128 v[204:207], v150 offset:36864
	ds_read_b128 v[208:211], v150 offset:37888
	ds_read_b128 v[212:215], v150 offset:38912
	ds_read_b128 v[216:219], v150 offset:39936
	s_waitcnt vmcnt(8)
	s_waitcnt lgkmcnt(0)
	s_barrier
	v_mfma_f32_16x16x32_bf16 v[126:129], v[154:157], v[188:191], v[126:129]
	v_mfma_f32_16x16x32_bf16 v[126:129], v[158:161], v[192:195], v[126:129]
	v_mfma_f32_16x16x32_bf16 v[122:125], v[168:171], v[192:195], v[122:125]
	v_mfma_f32_16x16x32_bf16 v[122:125], v[164:167], v[188:191], v[122:125]
	v_mfma_f32_16x16x32_bf16 v[114:117], v[164:167], v[196:199], v[114:117]
	v_mfma_f32_16x16x32_bf16 v[114:117], v[168:171], v[200:203], v[114:117]
	v_mfma_f32_16x16x32_bf16 v[118:121], v[158:161], v[200:203], v[118:121]
	v_mfma_f32_16x16x32_bf16 v[118:121], v[154:157], v[196:199], v[118:121]
	v_mfma_f32_16x16x32_bf16 v[102:105], v[154:157], v[204:207], v[102:105]
	v_mfma_f32_16x16x32_bf16 v[102:105], v[158:161], v[208:211], v[102:105]
	v_mfma_f32_16x16x32_bf16 v[98:101], v[168:171], v[208:211], v[98:101]
	v_mfma_f32_16x16x32_bf16 v[98:101], v[164:167], v[204:207], v[98:101]
	v_mfma_f32_16x16x32_bf16 v[82:85], v[164:167], v[212:215], v[82:85]
	v_mfma_f32_16x16x32_bf16 v[82:85], v[168:171], v[216:219], v[82:85]
	v_mfma_f32_16x16x32_bf16 v[86:89], v[158:161], v[216:219], v[86:89]
	v_mfma_f32_16x16x32_bf16 v[86:89], v[154:157], v[212:215], v[86:89]
	v_mfma_f32_16x16x32_bf16 v[70:73], v[172:175], v[212:215], v[70:73]
	v_mfma_f32_16x16x32_bf16 v[70:73], v[176:179], v[216:219], v[70:73]
	v_mfma_f32_16x16x32_bf16 v[66:69], v[184:187], v[216:219], v[66:69]
	v_mfma_f32_16x16x32_bf16 v[66:69], v[180:183], v[212:215], v[66:69]
	v_mfma_f32_16x16x32_bf16 v[74:77], v[180:183], v[204:207], v[74:77]
	v_mfma_f32_16x16x32_bf16 v[74:77], v[184:187], v[208:211], v[74:77]
	v_mfma_f32_16x16x32_bf16 v[78:81], v[176:179], v[208:211], v[78:81]
	v_mfma_f32_16x16x32_bf16 v[78:81], v[172:175], v[204:207], v[78:81]
	v_mfma_f32_16x16x32_bf16 v[94:97], v[172:175], v[196:199], v[94:97]
	v_mfma_f32_16x16x32_bf16 v[94:97], v[176:179], v[200:203], v[94:97]
	v_mfma_f32_16x16x32_bf16 v[90:93], v[184:187], v[200:203], v[90:93]
	v_mfma_f32_16x16x32_bf16 v[90:93], v[180:183], v[196:199], v[90:93]
	v_mfma_f32_16x16x32_bf16 v[106:109], v[180:183], v[188:191], v[106:109]
	v_mfma_f32_16x16x32_bf16 v[106:109], v[184:187], v[192:195], v[106:109]
	v_mfma_f32_16x16x32_bf16 v[110:113], v[176:179], v[192:195], v[110:113]
	v_mfma_f32_16x16x32_bf16 v[110:113], v[172:175], v[188:191], v[110:113]
	s_barrier
	s_mov_b32 m0, s47
	s_add_u32 s24, s24, 0x80
	s_addc_u32 s25, s25, 0
	global_load_lds_dwordx4 v132, s[24:25]
	s_mov_b32 m0, s48
	ds_read_b128 v[188:191], v150 offset:49152
	global_load_lds_dwordx4 v136, s[24:25]
	s_add_i32 s26, s46, s29
	s_mov_b32 m0, s26
	s_add_u32 s24, s24, 0x100000
	s_addc_u32 s25, s25, 0
	global_load_lds_dwordx4 v132, s[24:25]
	s_add_i32 m0, s26, 0x2000
	ds_read_b128 v[192:195], v150 offset:50176
	global_load_lds_dwordx4 v136, s[24:25]
	ds_read_b128 v[196:199], v150 offset:51200
	ds_read_b128 v[200:203], v150 offset:52224
	ds_read_b128 v[204:207], v150 offset:53248
	ds_read_b128 v[208:211], v150 offset:54272
	ds_read_b128 v[212:215], v150 offset:55296
	ds_read_b128 v[216:219], v150 offset:56320
	s_waitcnt vmcnt(6)
	s_waitcnt lgkmcnt(0)
	s_barrier
	v_mfma_f32_16x16x32_bf16 v[62:65], v[154:157], v[188:191], v[62:65]
	v_mfma_f32_16x16x32_bf16 v[62:65], v[158:161], v[192:195], v[62:65]
	v_mfma_f32_16x16x32_bf16 v[58:61], v[168:171], v[192:195], v[58:61]
	v_mfma_f32_16x16x32_bf16 v[58:61], v[164:167], v[188:191], v[58:61]
	v_mfma_f32_16x16x32_bf16 v[50:53], v[164:167], v[196:199], v[50:53]
	v_mfma_f32_16x16x32_bf16 v[50:53], v[168:171], v[200:203], v[50:53]
	v_mfma_f32_16x16x32_bf16 v[54:57], v[158:161], v[200:203], v[54:57]
	v_mfma_f32_16x16x32_bf16 v[54:57], v[154:157], v[196:199], v[54:57]
	v_mfma_f32_16x16x32_bf16 v[38:41], v[154:157], v[204:207], v[38:41]
	v_mfma_f32_16x16x32_bf16 v[38:41], v[158:161], v[208:211], v[38:41]
	v_mfma_f32_16x16x32_bf16 v[34:37], v[168:171], v[208:211], v[34:37]
	v_mfma_f32_16x16x32_bf16 v[34:37], v[164:167], v[204:207], v[34:37]
	v_mfma_f32_16x16x32_bf16 v[18:21], v[164:167], v[212:215], v[18:21]
	v_mfma_f32_16x16x32_bf16 v[18:21], v[168:171], v[216:219], v[18:21]
	v_mfma_f32_16x16x32_bf16 v[22:25], v[158:161], v[216:219], v[22:25]
	v_mfma_f32_16x16x32_bf16 v[22:25], v[154:157], v[212:215], v[22:25]
	v_mfma_f32_16x16x32_bf16 v[6:9], v[172:175], v[212:215], v[6:9]
	v_mfma_f32_16x16x32_bf16 v[6:9], v[176:179], v[216:219], v[6:9]
	v_mfma_f32_16x16x32_bf16 v[2:5], v[184:187], v[216:219], v[2:5]
	v_mfma_f32_16x16x32_bf16 v[2:5], v[180:183], v[212:215], v[2:5]
	v_mfma_f32_16x16x32_bf16 v[10:13], v[180:183], v[204:207], v[10:13]
	v_mfma_f32_16x16x32_bf16 v[10:13], v[184:187], v[208:211], v[10:13]
	v_mfma_f32_16x16x32_bf16 v[14:17], v[176:179], v[208:211], v[14:17]
	v_mfma_f32_16x16x32_bf16 v[14:17], v[172:175], v[204:207], v[14:17]
	v_mfma_f32_16x16x32_bf16 v[30:33], v[172:175], v[196:199], v[30:33]
	v_mfma_f32_16x16x32_bf16 v[30:33], v[176:179], v[200:203], v[30:33]
	v_mfma_f32_16x16x32_bf16 v[26:29], v[184:187], v[200:203], v[26:29]
	v_mfma_f32_16x16x32_bf16 v[26:29], v[180:183], v[196:199], v[26:29]
	v_mfma_f32_16x16x32_bf16 v[42:45], v[180:183], v[188:191], v[42:45]
	v_mfma_f32_16x16x32_bf16 v[42:45], v[184:187], v[192:195], v[42:45]
	v_mfma_f32_16x16x32_bf16 v[46:49], v[176:179], v[192:195], v[46:49]
	v_mfma_f32_16x16x32_bf16 v[46:49], v[172:175], v[188:191], v[46:49]
	s_barrier
	s_add_i32 s56, s56, 2
	s_add_u32 s22, s22, 0x100
	s_addc_u32 s23, s23, 0
	s_add_u32 s54, s54, 0x100
	s_addc_u32 s55, s55, 0

.LBB0_1008:
	s_add_i32 s37, s37, 1
	s_lshl_b32 s7, s37, 5
	s_add_i32 s7, s7, s3
	s_ashr_i32 s19, s7, 2
	s_cmp_lt_i32 s19, 16
	s_mov_b64 s[24:25], s[8:9]
	s_cselect_b64 s[8:9], -1, 0
	s_cmp_lt_i32 s7, 64
	s_mov_b64 s[22:23], s[10:11]
	s_cselect_b64 s[10:11], -1, 0
	s_and_b64 s[20:21], s[10:11], exec
	s_mov_b32 s46, s18
	s_cselect_b32 s18, s31, s18
	s_mov_b32 s45, s6
	s_cselect_b32 s6, s19, s6
	s_ashr_i32 s19, s18, 31
	s_and_b64 s[20:21], s[10:11], s[8:9]
	s_lshl_b64 s[8:9], s[18:19], 21
	v_readlane_b32 s0, v250, 46
	v_readlane_b32 s1, v250, 47
	s_add_u32 s10, s0, s8
	s_addc_u32 s11, s1, s9
	s_and_b64 s[8:9], s[20:21], exec
	s_cselect_b32 s19, s11, s23
	s_cselect_b32 s47, s10, s22
	s_ashr_i32 s7, s6, 31
	s_lshl_b64 s[8:9], s[6:7], 21
	v_readlane_b32 s0, v250, 40
	v_readlane_b32 s1, v250, 41
	s_add_u32 s8, s0, s8
	s_addc_u32 s9, s1, s9
	s_and_b64 s[26:27], s[20:21], exec
	s_cselect_b32 s7, s9, s25
	s_cselect_b32 s48, s8, s24
	s_add_u32 s22, s22, 0x100080
	s_addc_u32 s23, s23, 0
	s_add_u32 s49, s24, 0x100
	s_addc_u32 s50, s25, 0
	s_mov_b32 s51, -2
	s_waitcnt lgkmcnt(0)
	ds_read_b128 v[142:145], v155
	ds_read_b128 v[158:161], v155 offset:1024
	ds_read_b128 v[168:171], v155 offset:2048
	ds_read_b128 v[176:179], v155 offset:3072
	ds_read_b128 v[180:183], v156
	ds_read_b128 v[184:187], v156 offset:1024
	ds_read_b128 v[188:191], v156 offset:2048
	ds_read_b128 v[192:195], v156 offset:3072
	s_add_u32 s24, s22, 0xfff00080
	s_addc_u32 s25, s23, -1
	s_cmp_eq_u32 s51, 60
	s_cselect_b32 s27, s19, s25
	s_cselect_b32 s26, s47, s24
	s_cselect_b32 s25, s7, s50
	s_cselect_b32 s24, s48, s49
	s_mov_b32 m0, s40
	ds_read_b128 v[202:205], v157
	ds_read_b128 v[206:209], v157 offset:1024
	ds_read_b128 v[210:213], v157 offset:2048
	ds_read_b128 v[214:217], v157 offset:3072
	ds_read_b128 v[218:221], v157 offset:4096
	ds_read_b128 v[222:225], v157 offset:5120
	ds_read_b128 v[226:229], v157 offset:6144
	ds_read_b128 v[230:233], v157 offset:7168
	global_load_lds_dwordx4 v138, s[22:23]
	s_mov_b32 m0, s41
	s_nop 0
	global_load_lds_dwordx4 v140, s[22:23]
	s_waitcnt vmcnt(8)
	s_waitcnt lgkmcnt(0)
	s_barrier
	v_mfma_f32_16x16x32_bf16 v[126:129], v[142:145], v[202:205], 0
	v_mfma_f32_16x16x32_bf16 v[126:129], v[158:161], v[206:209], v[126:129]
	v_mfma_f32_16x16x32_bf16 v[122:125], v[176:179], v[206:209], 0
	v_mfma_f32_16x16x32_bf16 v[122:125], v[168:171], v[202:205], v[122:125]
	v_mfma_f32_16x16x32_bf16 v[106:109], v[168:171], v[210:213], 0
	v_mfma_f32_16x16x32_bf16 v[106:109], v[176:179], v[214:217], v[106:109]
	v_mfma_f32_16x16x32_bf16 v[110:113], v[158:161], v[214:217], 0
	v_mfma_f32_16x16x32_bf16 v[110:113], v[142:145], v[210:213], v[110:113]
	v_mfma_f32_16x16x32_bf16 v[94:97], v[142:145], v[218:221], 0
	v_mfma_f32_16x16x32_bf16 v[94:97], v[158:161], v[222:225], v[94:97]
	v_mfma_f32_16x16x32_bf16 v[90:93], v[176:179], v[222:225], 0
	v_mfma_f32_16x16x32_bf16 v[90:93], v[168:171], v[218:221], v[90:93]
	v_mfma_f32_16x16x32_bf16 v[74:77], v[168:171], v[226:229], 0
	v_mfma_f32_16x16x32_bf16 v[74:77], v[176:179], v[230:233], v[74:77]
	v_mfma_f32_16x16x32_bf16 v[78:81], v[158:161], v[230:233], 0
	v_mfma_f32_16x16x32_bf16 v[78:81], v[142:145], v[226:229], v[78:81]
	v_mfma_f32_16x16x32_bf16 v[70:73], v[180:183], v[226:229], 0
	v_mfma_f32_16x16x32_bf16 v[70:73], v[184:187], v[230:233], v[70:73]
	v_mfma_f32_16x16x32_bf16 v[66:69], v[192:195], v[230:233], 0
	v_mfma_f32_16x16x32_bf16 v[66:69], v[188:191], v[226:229], v[66:69]
	v_mfma_f32_16x16x32_bf16 v[82:85], v[188:191], v[218:221], 0
	v_mfma_f32_16x16x32_bf16 v[82:85], v[192:195], v[222:225], v[82:85]
	v_mfma_f32_16x16x32_bf16 v[86:89], v[184:187], v[222:225], 0
	v_mfma_f32_16x16x32_bf16 v[86:89], v[180:183], v[218:221], v[86:89]
	v_mfma_f32_16x16x32_bf16 v[102:105], v[180:183], v[210:213], 0
	v_mfma_f32_16x16x32_bf16 v[102:105], v[184:187], v[214:217], v[102:105]
	v_mfma_f32_16x16x32_bf16 v[98:101], v[192:195], v[214:217], 0
	v_mfma_f32_16x16x32_bf16 v[98:101], v[188:191], v[210:213], v[98:101]
	v_mfma_f32_16x16x32_bf16 v[114:117], v[188:191], v[202:205], 0
	v_mfma_f32_16x16x32_bf16 v[114:117], v[192:195], v[206:209], v[114:117]
	v_mfma_f32_16x16x32_bf16 v[118:121], v[184:187], v[206:209], 0
	v_mfma_f32_16x16x32_bf16 v[118:121], v[180:183], v[202:205], v[118:121]
	s_barrier
	s_mov_b32 m0, s42
	s_add_u32 s52, s24, 0x100000
	ds_read_b128 v[202:205], v157 offset:16384
	ds_read_b128 v[206:209], v157 offset:17408
	ds_read_b128 v[210:213], v157 offset:18432
	ds_read_b128 v[214:217], v157 offset:19456
	ds_read_b128 v[218:221], v157 offset:20480
	ds_read_b128 v[222:225], v157 offset:21504
	ds_read_b128 v[226:229], v157 offset:22528
	ds_read_b128 v[230:233], v157 offset:23552
	global_load_lds_dwordx4 v132, s[24:25]
	s_mov_b32 m0, s43
	s_addc_u32 s53, s25, 0
	global_load_lds_dwordx4 v136, s[24:25]
	s_mov_b32 m0, s44
	s_nop 0
	global_load_lds_dwordx4 v132, s[52:53]
	s_add_i32 m0, s44, 0x2000
	s_nop 0
	global_load_lds_dwordx4 v136, s[52:53]
	s_mov_b32 m0, s33
	s_nop 0
	global_load_lds_dwordx4 v130, s[26:27]
	s_mov_b32 m0, s34
	s_nop 0
	global_load_lds_dwordx4 v134, s[26:27]
	s_waitcnt vmcnt(8)
	s_waitcnt lgkmcnt(0)
	s_barrier
	v_mfma_f32_16x16x32_bf16 v[62:65], v[142:145], v[202:205], 0
	v_mfma_f32_16x16x32_bf16 v[62:65], v[158:161], v[206:209], v[62:65]
	v_mfma_f32_16x16x32_bf16 v[58:61], v[176:179], v[206:209], 0
	v_mfma_f32_16x16x32_bf16 v[58:61], v[168:171], v[202:205], v[58:61]
	v_mfma_f32_16x16x32_bf16 v[42:45], v[168:171], v[210:213], 0
	v_mfma_f32_16x16x32_bf16 v[42:45], v[176:179], v[214:217], v[42:45]
	v_mfma_f32_16x16x32_bf16 v[46:49], v[158:161], v[214:217], 0
	v_mfma_f32_16x16x32_bf16 v[46:49], v[142:145], v[210:213], v[46:49]
	v_mfma_f32_16x16x32_bf16 v[30:33], v[142:145], v[218:221], 0
	v_mfma_f32_16x16x32_bf16 v[30:33], v[158:161], v[222:225], v[30:33]
	v_mfma_f32_16x16x32_bf16 v[26:29], v[176:179], v[222:225], 0
	v_mfma_f32_16x16x32_bf16 v[26:29], v[168:171], v[218:221], v[26:29]
	v_mfma_f32_16x16x32_bf16 v[10:13], v[168:171], v[226:229], 0
	v_mfma_f32_16x16x32_bf16 v[10:13], v[176:179], v[230:233], v[10:13]
	v_mfma_f32_16x16x32_bf16 v[14:17], v[158:161], v[230:233], 0
	v_mfma_f32_16x16x32_bf16 v[14:17], v[142:145], v[226:229], v[14:17]
	v_mfma_f32_16x16x32_bf16 v[6:9], v[180:183], v[226:229], 0
	v_mfma_f32_16x16x32_bf16 v[6:9], v[184:187], v[230:233], v[6:9]
	v_mfma_f32_16x16x32_bf16 v[2:5], v[192:195], v[230:233], 0
	v_mfma_f32_16x16x32_bf16 v[2:5], v[188:191], v[226:229], v[2:5]
	v_mfma_f32_16x16x32_bf16 v[18:21], v[188:191], v[218:221], 0
	v_mfma_f32_16x16x32_bf16 v[18:21], v[192:195], v[222:225], v[18:21]
	v_mfma_f32_16x16x32_bf16 v[22:25], v[184:187], v[222:225], 0
	v_mfma_f32_16x16x32_bf16 v[22:25], v[180:183], v[218:221], v[22:25]
	v_mfma_f32_16x16x32_bf16 v[38:41], v[180:183], v[210:213], 0
	v_mfma_f32_16x16x32_bf16 v[38:41], v[184:187], v[214:217], v[38:41]
	v_mfma_f32_16x16x32_bf16 v[34:37], v[192:195], v[214:217], 0
	v_mfma_f32_16x16x32_bf16 v[34:37], v[188:191], v[210:213], v[34:37]
	v_mfma_f32_16x16x32_bf16 v[50:53], v[188:191], v[202:205], 0
	v_mfma_f32_16x16x32_bf16 v[50:53], v[192:195], v[206:209], v[50:53]
	v_mfma_f32_16x16x32_bf16 v[54:57], v[184:187], v[206:209], 0
	v_mfma_f32_16x16x32_bf16 v[54:57], v[180:183], v[202:205], v[54:57]
	s_barrier
	s_add_i32 s52, 0, 0x18000
	v_add_u32_e32 v166, s52, v153
	s_add_i32 s53, 0, 0x1c000
	ds_read_b128 v[142:145], v166
	ds_read_b128 v[158:161], v166 offset:1024
	ds_read_b128 v[168:171], v166 offset:2048
	ds_read_b128 v[176:179], v166 offset:3072
	v_add_u32_e32 v166, s53, v153
	ds_read_b128 v[180:183], v166
	ds_read_b128 v[184:187], v166 offset:1024
	ds_read_b128 v[188:191], v166 offset:2048
	ds_read_b128 v[192:195], v166 offset:3072
	s_add_u32 s26, s26, 0x100000
	s_addc_u32 s27, s27, 0
	s_mov_b32 m0, s35
	ds_read_b128 v[202:205], v157 offset:32768
	ds_read_b128 v[206:209], v157 offset:33792
	ds_read_b128 v[210:213], v157 offset:34816
	ds_read_b128 v[214:217], v157 offset:35840
	ds_read_b128 v[218:221], v157 offset:36864
	ds_read_b128 v[222:225], v157 offset:37888
	ds_read_b128 v[226:229], v157 offset:38912
	ds_read_b128 v[230:233], v157 offset:39936
	global_load_lds_dwordx4 v130, s[26:27]
	s_mov_b32 m0, s36
	s_nop 0
	global_load_lds_dwordx4 v134, s[26:27]
	s_waitcnt vmcnt(8)
	s_waitcnt lgkmcnt(0)
	s_barrier
	v_mfma_f32_16x16x32_bf16 v[126:129], v[142:145], v[202:205], v[126:129]
	v_mfma_f32_16x16x32_bf16 v[126:129], v[158:161], v[206:209], v[126:129]
	v_mfma_f32_16x16x32_bf16 v[122:125], v[176:179], v[206:209], v[122:125]
	v_mfma_f32_16x16x32_bf16 v[122:125], v[168:171], v[202:205], v[122:125]
	v_mfma_f32_16x16x32_bf16 v[106:109], v[168:171], v[210:213], v[106:109]
	v_mfma_f32_16x16x32_bf16 v[106:109], v[176:179], v[214:217], v[106:109]
	v_mfma_f32_16x16x32_bf16 v[110:113], v[158:161], v[214:217], v[110:113]
	v_mfma_f32_16x16x32_bf16 v[110:113], v[142:145], v[210:213], v[110:113]
	v_mfma_f32_16x16x32_bf16 v[94:97], v[142:145], v[218:221], v[94:97]
	v_mfma_f32_16x16x32_bf16 v[94:97], v[158:161], v[222:225], v[94:97]
	v_mfma_f32_16x16x32_bf16 v[90:93], v[176:179], v[222:225], v[90:93]
	v_mfma_f32_16x16x32_bf16 v[90:93], v[168:171], v[218:221], v[90:93]
	v_mfma_f32_16x16x32_bf16 v[74:77], v[168:171], v[226:229], v[74:77]
	v_mfma_f32_16x16x32_bf16 v[74:77], v[176:179], v[230:233], v[74:77]
	v_mfma_f32_16x16x32_bf16 v[78:81], v[158:161], v[230:233], v[78:81]
	v_mfma_f32_16x16x32_bf16 v[78:81], v[142:145], v[226:229], v[78:81]
	v_mfma_f32_16x16x32_bf16 v[70:73], v[180:183], v[226:229], v[70:73]
	v_mfma_f32_16x16x32_bf16 v[70:73], v[184:187], v[230:233], v[70:73]
	v_mfma_f32_16x16x32_bf16 v[66:69], v[192:195], v[230:233], v[66:69]
	v_mfma_f32_16x16x32_bf16 v[66:69], v[188:191], v[226:229], v[66:69]
	v_mfma_f32_16x16x32_bf16 v[82:85], v[188:191], v[218:221], v[82:85]
	v_mfma_f32_16x16x32_bf16 v[82:85], v[192:195], v[222:225], v[82:85]
	v_mfma_f32_16x16x32_bf16 v[86:89], v[184:187], v[222:225], v[86:89]
	v_mfma_f32_16x16x32_bf16 v[86:89], v[180:183], v[218:221], v[86:89]
	v_mfma_f32_16x16x32_bf16 v[102:105], v[180:183], v[210:213], v[102:105]
	v_mfma_f32_16x16x32_bf16 v[102:105], v[184:187], v[214:217], v[102:105]
	v_mfma_f32_16x16x32_bf16 v[98:101], v[192:195], v[214:217], v[98:101]
	v_mfma_f32_16x16x32_bf16 v[98:101], v[188:191], v[210:213], v[98:101]
	v_mfma_f32_16x16x32_bf16 v[114:117], v[188:191], v[202:205], v[114:117]
	v_mfma_f32_16x16x32_bf16 v[114:117], v[192:195], v[206:209], v[114:117]
	v_mfma_f32_16x16x32_bf16 v[118:121], v[184:187], v[206:209], v[118:121]
	v_mfma_f32_16x16x32_bf16 v[118:121], v[180:183], v[202:205], v[118:121]
	s_barrier
	s_add_u32 s98, s26, 0xfff00080
	s_addc_u32 s99, s27, -1
	s_add_u32 s24, s24, 0x80
	s_addc_u32 s25, s25, 0
	s_add_i32 s26, s52, s30
	s_mov_b32 m0, s26
	ds_read_b128 v[202:205], v157 offset:49152
	ds_read_b128 v[206:209], v157 offset:50176
	ds_read_b128 v[210:213], v157 offset:51200
	ds_read_b128 v[214:217], v157 offset:52224
	ds_read_b128 v[218:221], v157 offset:53248
	ds_read_b128 v[222:225], v157 offset:54272
	ds_read_b128 v[226:229], v157 offset:55296
	ds_read_b128 v[230:233], v157 offset:56320
	global_load_lds_dwordx4 v132, s[24:25]
	s_add_i32 m0, s26, 0x2000
	s_add_i32 s26, s53, s30
	global_load_lds_dwordx4 v136, s[24:25]
	s_add_u32 s24, s24, 0x100000
	s_addc_u32 s25, s25, 0
	s_mov_b32 m0, s26
	s_nop 0
	global_load_lds_dwordx4 v132, s[24:25]
	s_add_i32 m0, s26, 0x2000
	s_nop 0
	global_load_lds_dwordx4 v136, s[24:25]
	s_mov_b32 m0, s38
	s_nop 0
	global_load_lds_dwordx4 v130, s[98:99]
	s_mov_b32 m0, s39
	s_nop 0
	global_load_lds_dwordx4 v134, s[98:99]
	s_waitcnt vmcnt(8)
	s_waitcnt lgkmcnt(0)
	s_barrier
	v_mfma_f32_16x16x32_bf16 v[62:65], v[142:145], v[202:205], v[62:65]
	v_mfma_f32_16x16x32_bf16 v[62:65], v[158:161], v[206:209], v[62:65]
	v_mfma_f32_16x16x32_bf16 v[58:61], v[176:179], v[206:209], v[58:61]
	v_mfma_f32_16x16x32_bf16 v[58:61], v[168:171], v[202:205], v[58:61]
	v_mfma_f32_16x16x32_bf16 v[42:45], v[168:171], v[210:213], v[42:45]
	v_mfma_f32_16x16x32_bf16 v[42:45], v[176:179], v[214:217], v[42:45]
	v_mfma_f32_16x16x32_bf16 v[46:49], v[158:161], v[214:217], v[46:49]
	v_mfma_f32_16x16x32_bf16 v[46:49], v[142:145], v[210:213], v[46:49]
	v_mfma_f32_16x16x32_bf16 v[30:33], v[142:145], v[218:221], v[30:33]
	v_mfma_f32_16x16x32_bf16 v[30:33], v[158:161], v[222:225], v[30:33]
	v_mfma_f32_16x16x32_bf16 v[26:29], v[176:179], v[222:225], v[26:29]
	v_mfma_f32_16x16x32_bf16 v[26:29], v[168:171], v[218:221], v[26:29]
	v_mfma_f32_16x16x32_bf16 v[10:13], v[168:171], v[226:229], v[10:13]
	v_mfma_f32_16x16x32_bf16 v[10:13], v[176:179], v[230:233], v[10:13]
	v_mfma_f32_16x16x32_bf16 v[14:17], v[158:161], v[230:233], v[14:17]
	v_mfma_f32_16x16x32_bf16 v[14:17], v[142:145], v[226:229], v[14:17]
	v_mfma_f32_16x16x32_bf16 v[6:9], v[180:183], v[226:229], v[6:9]
	v_mfma_f32_16x16x32_bf16 v[6:9], v[184:187], v[230:233], v[6:9]
	v_mfma_f32_16x16x32_bf16 v[2:5], v[192:195], v[230:233], v[2:5]
	v_mfma_f32_16x16x32_bf16 v[2:5], v[188:191], v[226:229], v[2:5]
	v_mfma_f32_16x16x32_bf16 v[18:21], v[188:191], v[218:221], v[18:21]
	v_mfma_f32_16x16x32_bf16 v[18:21], v[192:195], v[222:225], v[18:21]
	v_mfma_f32_16x16x32_bf16 v[22:25], v[184:187], v[222:225], v[22:25]
	v_mfma_f32_16x16x32_bf16 v[22:25], v[180:183], v[218:221], v[22:25]
	v_mfma_f32_16x16x32_bf16 v[38:41], v[180:183], v[210:213], v[38:41]
	v_mfma_f32_16x16x32_bf16 v[38:41], v[184:187], v[214:217], v[38:41]
	v_mfma_f32_16x16x32_bf16 v[34:37], v[192:195], v[214:217], v[34:37]
	v_mfma_f32_16x16x32_bf16 v[34:37], v[188:191], v[210:213], v[34:37]
	v_mfma_f32_16x16x32_bf16 v[50:53], v[188:191], v[202:205], v[50:53]
	v_mfma_f32_16x16x32_bf16 v[50:53], v[192:195], v[206:209], v[50:53]
	v_mfma_f32_16x16x32_bf16 v[54:57], v[184:187], v[206:209], v[54:57]
	v_mfma_f32_16x16x32_bf16 v[54:57], v[180:183], v[202:205], v[54:57]
	s_barrier
	s_add_i32 s51, s51, 2
	s_add_u32 s22, s22, 0x100
	s_addc_u32 s23, s23, 0
	s_add_u32 s49, s49, 0x100
	s_addc_u32 s50, s50, 0

.LBB0_1171:
	s_add_i32 s36, s36, 1
	s_mov_b32 s52, s6
	s_lshl_b32 s6, s36, 5
	s_add_i32 s6, s6, s3
	s_mov_b64 s[22:23], s[8:9]
	s_lshl_b32 s8, s6, 3
	s_ashr_i32 s7, s6, 2
	s_add_i32 s8, s8, s39
	s_cmpk_lt_i32 s6, 0x158
	s_cselect_b32 s6, s7, s8
	s_mov_b32 s53, s26
	s_cselect_b32 s26, s40, 32
	s_cmpk_lt_i32 s6, 0x56
	s_cselect_b64 s[18:19], -1, 0
	s_lshl_b32 s7, s26, 21
	v_readlane_b32 s0, v250, 46
	s_mov_b64 s[20:21], s[10:11]
	v_readlane_b32 s1, v250, 47
	s_add_u32 s10, s0, s7
	s_addc_u32 s11, s1, 0
	s_and_b64 s[8:9], s[18:19], exec
	s_cselect_b32 s54, s11, s21
	s_cselect_b32 s55, s10, s20
	s_ashr_i32 s7, s6, 31
	s_lshl_b64 s[8:9], s[6:7], 21
	s_add_u32 s8, s27, s8
	s_addc_u32 s9, s30, s9
	s_and_b64 s[24:25], s[18:19], exec
	s_cselect_b32 s7, s9, s23
	s_cselect_b32 s56, s8, s22
	s_add_u32 s20, s20, 0x100080
	s_addc_u32 s21, s21, 0
	s_add_u32 s57, s22, 0x100
	s_addc_u32 s60, s23, 0
	s_mov_b32 s61, -2
	s_waitcnt lgkmcnt(0)
	s_add_u32 s62, s20, 0xfff00000
	s_addc_u32 s63, s21, -1
	s_mov_b32 m0, s37
	ds_read_b128 v[142:145], v148
	global_load_lds_dwordx4 v130, s[62:63]
	s_mov_b32 m0, s38
	ds_read_b128 v[154:157], v148 offset:1024
	global_load_lds_dwordx4 v134, s[62:63]
	s_mov_b32 m0, s42
	ds_read_b128 v[158:161], v148 offset:2048
	global_load_lds_dwordx4 v138, s[20:21]
	s_mov_b32 m0, s43
	ds_read_b128 v[168:171], v148 offset:3072
	global_load_lds_dwordx4 v140, s[20:21]
	ds_read_b128 v[176:179], v149
	ds_read_b128 v[180:183], v149 offset:1024
	ds_read_b128 v[184:187], v149 offset:2048
	ds_read_b128 v[188:191], v149 offset:3072
	s_add_u32 s22, s20, 0xfff00080
	s_addc_u32 s23, s21, -1
	s_cmp_eq_u32 s61, 60
	s_cselect_b32 s25, s54, s23
	s_cselect_b32 s24, s55, s22
	s_cselect_b32 s23, s7, s60
	s_cselect_b32 s22, s56, s57
	ds_read_b128 v[192:195], v150
	ds_read_b128 v[202:205], v150 offset:1024
	ds_read_b128 v[206:209], v150 offset:2048
	ds_read_b128 v[210:213], v150 offset:3072
	ds_read_b128 v[214:217], v150 offset:4096
	ds_read_b128 v[218:221], v150 offset:5120
	ds_read_b128 v[222:225], v150 offset:6144
	ds_read_b128 v[226:229], v150 offset:7168
	s_waitcnt vmcnt(8)
	s_waitcnt lgkmcnt(0)
	s_barrier
	v_mfma_f32_16x16x32_bf16 v[126:129], v[142:145], v[192:195], 0
	v_mfma_f32_16x16x32_bf16 v[126:129], v[154:157], v[202:205], v[126:129]
	v_mfma_f32_16x16x32_bf16 v[118:121], v[168:171], v[202:205], 0
	v_mfma_f32_16x16x32_bf16 v[118:121], v[158:161], v[192:195], v[118:121]
	v_mfma_f32_16x16x32_bf16 v[102:105], v[158:161], v[206:209], 0
	v_mfma_f32_16x16x32_bf16 v[102:105], v[168:171], v[210:213], v[102:105]
	v_mfma_f32_16x16x32_bf16 v[110:113], v[154:157], v[210:213], 0
	v_mfma_f32_16x16x32_bf16 v[110:113], v[142:145], v[206:209], v[110:113]
	v_mfma_f32_16x16x32_bf16 v[94:97], v[142:145], v[214:217], 0
	v_mfma_f32_16x16x32_bf16 v[94:97], v[154:157], v[218:221], v[94:97]
	v_mfma_f32_16x16x32_bf16 v[86:89], v[168:171], v[218:221], 0
	v_mfma_f32_16x16x32_bf16 v[86:89], v[158:161], v[214:217], v[86:89]
	v_mfma_f32_16x16x32_bf16 v[70:73], v[158:161], v[222:225], 0
	v_mfma_f32_16x16x32_bf16 v[70:73], v[168:171], v[226:229], v[70:73]
	v_mfma_f32_16x16x32_bf16 v[78:81], v[154:157], v[226:229], 0
	v_mfma_f32_16x16x32_bf16 v[78:81], v[142:145], v[222:225], v[78:81]
	v_mfma_f32_16x16x32_bf16 v[74:77], v[176:179], v[222:225], 0
	v_mfma_f32_16x16x32_bf16 v[74:77], v[180:183], v[226:229], v[74:77]
	v_mfma_f32_16x16x32_bf16 v[66:69], v[188:191], v[226:229], 0
	v_mfma_f32_16x16x32_bf16 v[66:69], v[184:187], v[222:225], v[66:69]
	v_mfma_f32_16x16x32_bf16 v[82:85], v[184:187], v[214:217], 0
	v_mfma_f32_16x16x32_bf16 v[82:85], v[188:191], v[218:221], v[82:85]
	v_mfma_f32_16x16x32_bf16 v[90:93], v[180:183], v[218:221], 0
	v_mfma_f32_16x16x32_bf16 v[90:93], v[176:179], v[214:217], v[90:93]
	v_mfma_f32_16x16x32_bf16 v[106:109], v[176:179], v[206:209], 0
	v_mfma_f32_16x16x32_bf16 v[106:109], v[180:183], v[210:213], v[106:109]
	v_mfma_f32_16x16x32_bf16 v[98:101], v[188:191], v[210:213], 0
	v_mfma_f32_16x16x32_bf16 v[98:101], v[184:187], v[206:209], v[98:101]
	v_mfma_f32_16x16x32_bf16 v[114:117], v[184:187], v[192:195], 0
	v_mfma_f32_16x16x32_bf16 v[114:117], v[188:191], v[202:205], v[114:117]
	v_mfma_f32_16x16x32_bf16 v[122:125], v[180:183], v[202:205], 0
	v_mfma_f32_16x16x32_bf16 v[122:125], v[176:179], v[192:195], v[122:125]
	s_barrier
	s_mov_b32 m0, s44
	s_add_u32 s62, s22, 0x100000
	global_load_lds_dwordx4 v132, s[22:23]
	s_mov_b32 m0, s45
	s_addc_u32 s63, s23, 0
	global_load_lds_dwordx4 v136, s[22:23]
	s_mov_b32 m0, s46
	ds_read_b128 v[192:195], v150 offset:16384
	global_load_lds_dwordx4 v132, s[62:63]
	s_mov_b32 m0, s47
	ds_read_b128 v[202:205], v150 offset:17408
	global_load_lds_dwordx4 v136, s[62:63]
	ds_read_b128 v[206:209], v150 offset:18432
	ds_read_b128 v[210:213], v150 offset:19456
	ds_read_b128 v[214:217], v150 offset:20480
	ds_read_b128 v[218:221], v150 offset:21504
	ds_read_b128 v[222:225], v150 offset:22528
	ds_read_b128 v[226:229], v150 offset:23552
	s_waitcnt vmcnt(6)
	s_waitcnt lgkmcnt(0)
	s_barrier
	v_mfma_f32_16x16x32_bf16 v[62:65], v[142:145], v[192:195], 0
	v_mfma_f32_16x16x32_bf16 v[62:65], v[154:157], v[202:205], v[62:65]
	v_mfma_f32_16x16x32_bf16 v[54:57], v[168:171], v[202:205], 0
	v_mfma_f32_16x16x32_bf16 v[54:57], v[158:161], v[192:195], v[54:57]
	v_mfma_f32_16x16x32_bf16 v[38:41], v[158:161], v[206:209], 0
	v_mfma_f32_16x16x32_bf16 v[38:41], v[168:171], v[210:213], v[38:41]
	v_mfma_f32_16x16x32_bf16 v[46:49], v[154:157], v[210:213], 0
	v_mfma_f32_16x16x32_bf16 v[46:49], v[142:145], v[206:209], v[46:49]
	v_mfma_f32_16x16x32_bf16 v[30:33], v[142:145], v[214:217], 0
	v_mfma_f32_16x16x32_bf16 v[30:33], v[154:157], v[218:221], v[30:33]
	v_mfma_f32_16x16x32_bf16 v[22:25], v[168:171], v[218:221], 0
	v_mfma_f32_16x16x32_bf16 v[22:25], v[158:161], v[214:217], v[22:25]
	v_mfma_f32_16x16x32_bf16 v[6:9], v[158:161], v[222:225], 0
	v_mfma_f32_16x16x32_bf16 v[6:9], v[168:171], v[226:229], v[6:9]
	v_mfma_f32_16x16x32_bf16 v[14:17], v[154:157], v[226:229], 0
	v_mfma_f32_16x16x32_bf16 v[14:17], v[142:145], v[222:225], v[14:17]
	v_mfma_f32_16x16x32_bf16 v[10:13], v[176:179], v[222:225], 0
	v_mfma_f32_16x16x32_bf16 v[10:13], v[180:183], v[226:229], v[10:13]
	v_mfma_f32_16x16x32_bf16 v[2:5], v[188:191], v[226:229], 0
	v_mfma_f32_16x16x32_bf16 v[2:5], v[184:187], v[222:225], v[2:5]
	v_mfma_f32_16x16x32_bf16 v[18:21], v[184:187], v[214:217], 0
	v_mfma_f32_16x16x32_bf16 v[18:21], v[188:191], v[218:221], v[18:21]
	v_mfma_f32_16x16x32_bf16 v[26:29], v[180:183], v[218:221], 0
	v_mfma_f32_16x16x32_bf16 v[26:29], v[176:179], v[214:217], v[26:29]
	v_mfma_f32_16x16x32_bf16 v[42:45], v[176:179], v[206:209], 0
	v_mfma_f32_16x16x32_bf16 v[42:45], v[180:183], v[210:213], v[42:45]
	v_mfma_f32_16x16x32_bf16 v[34:37], v[188:191], v[210:213], 0
	v_mfma_f32_16x16x32_bf16 v[34:37], v[184:187], v[206:209], v[34:37]
	v_mfma_f32_16x16x32_bf16 v[50:53], v[184:187], v[192:195], 0
	v_mfma_f32_16x16x32_bf16 v[50:53], v[188:191], v[202:205], v[50:53]
	v_mfma_f32_16x16x32_bf16 v[58:61], v[180:183], v[202:205], 0
	v_mfma_f32_16x16x32_bf16 v[58:61], v[176:179], v[192:195], v[58:61]
	s_barrier
	s_mov_b32 m0, s31
	ds_read_b128 v[142:145], v151
	global_load_lds_dwordx4 v130, s[24:25]
	s_mov_b32 m0, s33
	ds_read_b128 v[154:157], v151 offset:1024
	global_load_lds_dwordx4 v134, s[24:25]
	s_add_u32 s24, s24, 0x100000
	s_addc_u32 s25, s25, 0
	s_mov_b32 m0, s34
	ds_read_b128 v[158:161], v151 offset:2048
	global_load_lds_dwordx4 v130, s[24:25]
	s_mov_b32 m0, s35
	ds_read_b128 v[168:171], v151 offset:3072
	global_load_lds_dwordx4 v134, s[24:25]
	ds_read_b128 v[176:179], v152
	ds_read_b128 v[180:183], v152 offset:1024
	ds_read_b128 v[184:187], v152 offset:2048
	ds_read_b128 v[188:191], v152 offset:3072
	ds_read_b128 v[192:195], v150 offset:32768
	ds_read_b128 v[202:205], v150 offset:33792
	ds_read_b128 v[206:209], v150 offset:34816
	ds_read_b128 v[210:213], v150 offset:35840
	ds_read_b128 v[214:217], v150 offset:36864
	ds_read_b128 v[218:221], v150 offset:37888
	ds_read_b128 v[222:225], v150 offset:38912
	ds_read_b128 v[226:229], v150 offset:39936
	s_waitcnt vmcnt(8)
	s_waitcnt lgkmcnt(0)
	s_barrier
	v_mfma_f32_16x16x32_bf16 v[126:129], v[142:145], v[192:195], v[126:129]
	v_mfma_f32_16x16x32_bf16 v[126:129], v[154:157], v[202:205], v[126:129]
	v_mfma_f32_16x16x32_bf16 v[118:121], v[168:171], v[202:205], v[118:121]
	v_mfma_f32_16x16x32_bf16 v[118:121], v[158:161], v[192:195], v[118:121]
	v_mfma_f32_16x16x32_bf16 v[102:105], v[158:161], v[206:209], v[102:105]
	v_mfma_f32_16x16x32_bf16 v[102:105], v[168:171], v[210:213], v[102:105]
	v_mfma_f32_16x16x32_bf16 v[110:113], v[154:157], v[210:213], v[110:113]
	v_mfma_f32_16x16x32_bf16 v[110:113], v[142:145], v[206:209], v[110:113]
	v_mfma_f32_16x16x32_bf16 v[94:97], v[142:145], v[214:217], v[94:97]
	v_mfma_f32_16x16x32_bf16 v[94:97], v[154:157], v[218:221], v[94:97]
	v_mfma_f32_16x16x32_bf16 v[86:89], v[168:171], v[218:221], v[86:89]
	v_mfma_f32_16x16x32_bf16 v[86:89], v[158:161], v[214:217], v[86:89]
	v_mfma_f32_16x16x32_bf16 v[70:73], v[158:161], v[222:225], v[70:73]
	v_mfma_f32_16x16x32_bf16 v[70:73], v[168:171], v[226:229], v[70:73]
	v_mfma_f32_16x16x32_bf16 v[78:81], v[154:157], v[226:229], v[78:81]
	v_mfma_f32_16x16x32_bf16 v[78:81], v[142:145], v[222:225], v[78:81]
	v_mfma_f32_16x16x32_bf16 v[74:77], v[176:179], v[222:225], v[74:77]
	v_mfma_f32_16x16x32_bf16 v[74:77], v[180:183], v[226:229], v[74:77]
	v_mfma_f32_16x16x32_bf16 v[66:69], v[188:191], v[226:229], v[66:69]
	v_mfma_f32_16x16x32_bf16 v[66:69], v[184:187], v[222:225], v[66:69]
	v_mfma_f32_16x16x32_bf16 v[82:85], v[184:187], v[214:217], v[82:85]
	v_mfma_f32_16x16x32_bf16 v[82:85], v[188:191], v[218:221], v[82:85]
	v_mfma_f32_16x16x32_bf16 v[90:93], v[180:183], v[218:221], v[90:93]
	v_mfma_f32_16x16x32_bf16 v[90:93], v[176:179], v[214:217], v[90:93]
	v_mfma_f32_16x16x32_bf16 v[106:109], v[176:179], v[206:209], v[106:109]
	v_mfma_f32_16x16x32_bf16 v[106:109], v[180:183], v[210:213], v[106:109]
	v_mfma_f32_16x16x32_bf16 v[98:101], v[188:191], v[210:213], v[98:101]
	v_mfma_f32_16x16x32_bf16 v[98:101], v[184:187], v[206:209], v[98:101]
	v_mfma_f32_16x16x32_bf16 v[114:117], v[184:187], v[192:195], v[114:117]
	v_mfma_f32_16x16x32_bf16 v[114:117], v[188:191], v[202:205], v[114:117]
	v_mfma_f32_16x16x32_bf16 v[122:125], v[180:183], v[202:205], v[122:125]
	v_mfma_f32_16x16x32_bf16 v[122:125], v[176:179], v[192:195], v[122:125]
	s_barrier
	s_mov_b32 m0, s48
	s_add_u32 s22, s22, 0x80
	s_addc_u32 s23, s23, 0
	global_load_lds_dwordx4 v132, s[22:23]
	s_mov_b32 m0, s49
	ds_read_b128 v[192:195], v150 offset:49152
	global_load_lds_dwordx4 v136, s[22:23]
	s_mov_b32 m0, s50
	s_add_u32 s22, s22, 0x100000
	s_addc_u32 s23, s23, 0
	global_load_lds_dwordx4 v132, s[22:23]
	s_mov_b32 m0, s51
	ds_read_b128 v[202:205], v150 offset:50176
	global_load_lds_dwordx4 v136, s[22:23]
	ds_read_b128 v[206:209], v150 offset:51200
	ds_read_b128 v[210:213], v150 offset:52224
	ds_read_b128 v[214:217], v150 offset:53248
	ds_read_b128 v[218:221], v150 offset:54272
	ds_read_b128 v[222:225], v150 offset:55296
	ds_read_b128 v[226:229], v150 offset:56320
	s_waitcnt vmcnt(6)
	s_waitcnt lgkmcnt(0)
	s_barrier
	v_mfma_f32_16x16x32_bf16 v[62:65], v[142:145], v[192:195], v[62:65]
	v_mfma_f32_16x16x32_bf16 v[62:65], v[154:157], v[202:205], v[62:65]
	v_mfma_f32_16x16x32_bf16 v[54:57], v[168:171], v[202:205], v[54:57]
	v_mfma_f32_16x16x32_bf16 v[54:57], v[158:161], v[192:195], v[54:57]
	v_mfma_f32_16x16x32_bf16 v[38:41], v[158:161], v[206:209], v[38:41]
	v_mfma_f32_16x16x32_bf16 v[38:41], v[168:171], v[210:213], v[38:41]
	v_mfma_f32_16x16x32_bf16 v[46:49], v[154:157], v[210:213], v[46:49]
	v_mfma_f32_16x16x32_bf16 v[46:49], v[142:145], v[206:209], v[46:49]
	v_mfma_f32_16x16x32_bf16 v[30:33], v[142:145], v[214:217], v[30:33]
	v_mfma_f32_16x16x32_bf16 v[30:33], v[154:157], v[218:221], v[30:33]
	v_mfma_f32_16x16x32_bf16 v[22:25], v[168:171], v[218:221], v[22:25]
	v_mfma_f32_16x16x32_bf16 v[22:25], v[158:161], v[214:217], v[22:25]
	v_mfma_f32_16x16x32_bf16 v[6:9], v[158:161], v[222:225], v[6:9]
	v_mfma_f32_16x16x32_bf16 v[6:9], v[168:171], v[226:229], v[6:9]
	v_mfma_f32_16x16x32_bf16 v[14:17], v[154:157], v[226:229], v[14:17]
	v_mfma_f32_16x16x32_bf16 v[14:17], v[142:145], v[222:225], v[14:17]
	v_mfma_f32_16x16x32_bf16 v[10:13], v[176:179], v[222:225], v[10:13]
	v_mfma_f32_16x16x32_bf16 v[10:13], v[180:183], v[226:229], v[10:13]
	v_mfma_f32_16x16x32_bf16 v[2:5], v[188:191], v[226:229], v[2:5]
	v_mfma_f32_16x16x32_bf16 v[2:5], v[184:187], v[222:225], v[2:5]
	v_mfma_f32_16x16x32_bf16 v[18:21], v[184:187], v[214:217], v[18:21]
	v_mfma_f32_16x16x32_bf16 v[18:21], v[188:191], v[218:221], v[18:21]
	v_mfma_f32_16x16x32_bf16 v[26:29], v[180:183], v[218:221], v[26:29]
	v_mfma_f32_16x16x32_bf16 v[26:29], v[176:179], v[214:217], v[26:29]
	v_mfma_f32_16x16x32_bf16 v[42:45], v[176:179], v[206:209], v[42:45]
	v_mfma_f32_16x16x32_bf16 v[42:45], v[180:183], v[210:213], v[42:45]
	v_mfma_f32_16x16x32_bf16 v[34:37], v[188:191], v[210:213], v[34:37]
	v_mfma_f32_16x16x32_bf16 v[34:37], v[184:187], v[206:209], v[34:37]
	v_mfma_f32_16x16x32_bf16 v[50:53], v[184:187], v[192:195], v[50:53]
	v_mfma_f32_16x16x32_bf16 v[50:53], v[188:191], v[202:205], v[50:53]
	v_mfma_f32_16x16x32_bf16 v[58:61], v[180:183], v[202:205], v[58:61]
	v_mfma_f32_16x16x32_bf16 v[58:61], v[176:179], v[192:195], v[58:61]
	s_barrier
	s_add_i32 s61, s61, 2
	s_add_u32 s20, s20, 0x100
	s_addc_u32 s21, s21, 0
	s_add_u32 s57, s57, 0x100
	s_addc_u32 s60, s60, 0

.LBB0_1417:
	s_and_b64 s[18:19], s[18:19], exec
	s_cselect_b32 s19, s9, s23
	s_cselect_b32 s18, s8, s22
	s_add_u32 s22, s22, 0x2b0080
	s_addc_u32 s23, s23, 0
	s_add_u32 s53, s24, 0x100
	s_addc_u32 s54, s25, 0
	s_mov_b32 s55, -2
	s_waitcnt lgkmcnt(0)
	s_add_u32 s56, s22, 0xffd50000
	s_addc_u32 s57, s23, -1
	s_mov_b32 m0, s40
	ds_read_b128 v[142:145], v156
	global_load_lds_dwordx4 v130, s[56:57]
	s_mov_b32 m0, s41
	ds_read_b128 v[168:171], v156 offset:1024
	global_load_lds_dwordx4 v134, s[56:57]
	s_mov_b32 m0, s42
	ds_read_b128 v[176:179], v156 offset:2048
	global_load_lds_dwordx4 v138, s[22:23]
	s_mov_b32 m0, s43
	ds_read_b128 v[180:183], v156 offset:3072
	global_load_lds_dwordx4 v140, s[22:23]
	ds_read_b128 v[184:187], v157
	ds_read_b128 v[188:191], v157 offset:1024
	ds_read_b128 v[192:195], v157 offset:2048
	ds_read_b128 v[204:207], v157 offset:3072
	s_add_u32 s24, s22, 0xffd50080
	s_addc_u32 s25, s23, -1
	s_cmpk_eq_i32 s55, 0xa8
	s_cselect_b32 s27, s19, s25
	s_cselect_b32 s26, s18, s24
	s_cselect_b32 s25, s17, s54
	s_cselect_b32 s24, s16, s53
	ds_read_b128 v[208:211], v158
	ds_read_b128 v[212:215], v158 offset:1024
	ds_read_b128 v[216:219], v158 offset:2048
	ds_read_b128 v[220:223], v158 offset:3072
	ds_read_b128 v[224:227], v158 offset:4096
	ds_read_b128 v[228:231], v158 offset:5120
	ds_read_b128 v[232:235], v158 offset:6144
	ds_read_b128 v[236:239], v158 offset:7168
	s_waitcnt vmcnt(8)
	s_waitcnt lgkmcnt(0)
	s_barrier
	v_mfma_f32_16x16x32_bf16 v[126:129], v[142:145], v[208:211], 0
	v_mfma_f32_16x16x32_bf16 v[126:129], v[168:171], v[212:215], v[126:129]
	v_mfma_f32_16x16x32_bf16 v[122:125], v[180:183], v[212:215], 0
	v_mfma_f32_16x16x32_bf16 v[122:125], v[176:179], v[208:211], v[122:125]
	v_mfma_f32_16x16x32_bf16 v[106:109], v[176:179], v[216:219], 0
	v_mfma_f32_16x16x32_bf16 v[106:109], v[180:183], v[220:223], v[106:109]
	v_mfma_f32_16x16x32_bf16 v[110:113], v[168:171], v[220:223], 0
	v_mfma_f32_16x16x32_bf16 v[110:113], v[142:145], v[216:219], v[110:113]
	v_mfma_f32_16x16x32_bf16 v[94:97], v[142:145], v[224:227], 0
	v_mfma_f32_16x16x32_bf16 v[94:97], v[168:171], v[228:231], v[94:97]
	v_mfma_f32_16x16x32_bf16 v[90:93], v[180:183], v[228:231], 0
	v_mfma_f32_16x16x32_bf16 v[90:93], v[176:179], v[224:227], v[90:93]
	v_mfma_f32_16x16x32_bf16 v[74:77], v[176:179], v[232:235], 0
	v_mfma_f32_16x16x32_bf16 v[74:77], v[180:183], v[236:239], v[74:77]
	v_mfma_f32_16x16x32_bf16 v[78:81], v[168:171], v[236:239], 0
	v_mfma_f32_16x16x32_bf16 v[78:81], v[142:145], v[232:235], v[78:81]
	v_mfma_f32_16x16x32_bf16 v[70:73], v[184:187], v[232:235], 0
	v_mfma_f32_16x16x32_bf16 v[70:73], v[188:191], v[236:239], v[70:73]
	v_mfma_f32_16x16x32_bf16 v[66:69], v[204:207], v[236:239], 0
	v_mfma_f32_16x16x32_bf16 v[66:69], v[192:195], v[232:235], v[66:69]
	v_mfma_f32_16x16x32_bf16 v[82:85], v[192:195], v[224:227], 0
	v_mfma_f32_16x16x32_bf16 v[82:85], v[204:207], v[228:231], v[82:85]
	v_mfma_f32_16x16x32_bf16 v[86:89], v[188:191], v[228:231], 0
	v_mfma_f32_16x16x32_bf16 v[86:89], v[184:187], v[224:227], v[86:89]
	v_mfma_f32_16x16x32_bf16 v[102:105], v[184:187], v[216:219], 0
	v_mfma_f32_16x16x32_bf16 v[102:105], v[188:191], v[220:223], v[102:105]
	v_mfma_f32_16x16x32_bf16 v[98:101], v[204:207], v[220:223], 0
	v_mfma_f32_16x16x32_bf16 v[98:101], v[192:195], v[216:219], v[98:101]
	v_mfma_f32_16x16x32_bf16 v[114:117], v[192:195], v[208:211], 0
	v_mfma_f32_16x16x32_bf16 v[114:117], v[204:207], v[212:215], v[114:117]
	v_mfma_f32_16x16x32_bf16 v[118:121], v[188:191], v[212:215], 0
	v_mfma_f32_16x16x32_bf16 v[118:121], v[184:187], v[208:211], v[118:121]
	s_barrier
	s_mov_b32 m0, s44
	s_add_u32 s56, s24, 0x2b0000
	global_load_lds_dwordx4 v132, s[24:25]
	s_mov_b32 m0, s45
	s_addc_u32 s57, s25, 0
	global_load_lds_dwordx4 v136, s[24:25]
	s_mov_b32 m0, s46
	ds_read_b128 v[208:211], v158 offset:16384
	global_load_lds_dwordx4 v132, s[56:57]
	s_mov_b32 m0, s47
	ds_read_b128 v[212:215], v158 offset:17408
	global_load_lds_dwordx4 v136, s[56:57]
	ds_read_b128 v[216:219], v158 offset:18432
	ds_read_b128 v[220:223], v158 offset:19456
	ds_read_b128 v[224:227], v158 offset:20480
	ds_read_b128 v[228:231], v158 offset:21504
	ds_read_b128 v[232:235], v158 offset:22528
	ds_read_b128 v[236:239], v158 offset:23552
	s_waitcnt vmcnt(6)
	s_waitcnt lgkmcnt(0)
	s_barrier
	v_mfma_f32_16x16x32_bf16 v[62:65], v[142:145], v[208:211], 0
	v_mfma_f32_16x16x32_bf16 v[62:65], v[168:171], v[212:215], v[62:65]
	v_mfma_f32_16x16x32_bf16 v[58:61], v[180:183], v[212:215], 0
	v_mfma_f32_16x16x32_bf16 v[58:61], v[176:179], v[208:211], v[58:61]
	v_mfma_f32_16x16x32_bf16 v[42:45], v[176:179], v[216:219], 0
	v_mfma_f32_16x16x32_bf16 v[42:45], v[180:183], v[220:223], v[42:45]
	v_mfma_f32_16x16x32_bf16 v[46:49], v[168:171], v[220:223], 0
	v_mfma_f32_16x16x32_bf16 v[46:49], v[142:145], v[216:219], v[46:49]
	v_mfma_f32_16x16x32_bf16 v[30:33], v[142:145], v[224:227], 0
	v_mfma_f32_16x16x32_bf16 v[30:33], v[168:171], v[228:231], v[30:33]
	v_mfma_f32_16x16x32_bf16 v[26:29], v[180:183], v[228:231], 0
	v_mfma_f32_16x16x32_bf16 v[26:29], v[176:179], v[224:227], v[26:29]
	v_mfma_f32_16x16x32_bf16 v[10:13], v[176:179], v[232:235], 0
	v_mfma_f32_16x16x32_bf16 v[10:13], v[180:183], v[236:239], v[10:13]
	v_mfma_f32_16x16x32_bf16 v[14:17], v[168:171], v[236:239], 0
	v_mfma_f32_16x16x32_bf16 v[14:17], v[142:145], v[232:235], v[14:17]
	v_mfma_f32_16x16x32_bf16 v[6:9], v[184:187], v[232:235], 0
	v_mfma_f32_16x16x32_bf16 v[6:9], v[188:191], v[236:239], v[6:9]
	v_mfma_f32_16x16x32_bf16 v[2:5], v[204:207], v[236:239], 0
	v_mfma_f32_16x16x32_bf16 v[2:5], v[192:195], v[232:235], v[2:5]
	v_mfma_f32_16x16x32_bf16 v[18:21], v[192:195], v[224:227], 0
	v_mfma_f32_16x16x32_bf16 v[18:21], v[204:207], v[228:231], v[18:21]
	v_mfma_f32_16x16x32_bf16 v[22:25], v[188:191], v[228:231], 0
	v_mfma_f32_16x16x32_bf16 v[22:25], v[184:187], v[224:227], v[22:25]
	v_mfma_f32_16x16x32_bf16 v[38:41], v[184:187], v[216:219], 0
	v_mfma_f32_16x16x32_bf16 v[38:41], v[188:191], v[220:223], v[38:41]
	v_mfma_f32_16x16x32_bf16 v[34:37], v[204:207], v[220:223], 0
	v_mfma_f32_16x16x32_bf16 v[34:37], v[192:195], v[216:219], v[34:37]
	v_mfma_f32_16x16x32_bf16 v[50:53], v[192:195], v[208:211], 0
	v_mfma_f32_16x16x32_bf16 v[50:53], v[204:207], v[212:215], v[50:53]
	v_mfma_f32_16x16x32_bf16 v[54:57], v[188:191], v[212:215], 0
	v_mfma_f32_16x16x32_bf16 v[54:57], v[184:187], v[208:211], v[54:57]
	s_barrier
	s_mov_b32 m0, s35
	ds_read_b128 v[142:145], v159
	global_load_lds_dwordx4 v130, s[26:27]
	s_mov_b32 m0, s36
	ds_read_b128 v[168:171], v159 offset:1024
	global_load_lds_dwordx4 v134, s[26:27]
	s_add_u32 s26, s26, 0x2b0000
	s_addc_u32 s27, s27, 0
	s_mov_b32 m0, s37
	ds_read_b128 v[176:179], v159 offset:2048
	global_load_lds_dwordx4 v130, s[26:27]
	s_mov_b32 m0, s38
	ds_read_b128 v[180:183], v159 offset:3072
	global_load_lds_dwordx4 v134, s[26:27]
	ds_read_b128 v[184:187], v160
	ds_read_b128 v[188:191], v160 offset:1024
	ds_read_b128 v[192:195], v160 offset:2048
	ds_read_b128 v[204:207], v160 offset:3072
	ds_read_b128 v[208:211], v158 offset:32768
	ds_read_b128 v[212:215], v158 offset:33792
	ds_read_b128 v[216:219], v158 offset:34816
	ds_read_b128 v[220:223], v158 offset:35840
	ds_read_b128 v[224:227], v158 offset:36864
	ds_read_b128 v[228:231], v158 offset:37888
	ds_read_b128 v[232:235], v158 offset:38912
	ds_read_b128 v[236:239], v158 offset:39936
	s_waitcnt vmcnt(8)
	s_waitcnt lgkmcnt(0)
	s_barrier
	v_mfma_f32_16x16x32_bf16 v[126:129], v[142:145], v[208:211], v[126:129]
	v_mfma_f32_16x16x32_bf16 v[126:129], v[168:171], v[212:215], v[126:129]
	v_mfma_f32_16x16x32_bf16 v[122:125], v[180:183], v[212:215], v[122:125]
	v_mfma_f32_16x16x32_bf16 v[122:125], v[176:179], v[208:211], v[122:125]
	v_mfma_f32_16x16x32_bf16 v[106:109], v[176:179], v[216:219], v[106:109]
	v_mfma_f32_16x16x32_bf16 v[106:109], v[180:183], v[220:223], v[106:109]
	v_mfma_f32_16x16x32_bf16 v[110:113], v[168:171], v[220:223], v[110:113]
	v_mfma_f32_16x16x32_bf16 v[110:113], v[142:145], v[216:219], v[110:113]
	v_mfma_f32_16x16x32_bf16 v[94:97], v[142:145], v[224:227], v[94:97]
	v_mfma_f32_16x16x32_bf16 v[94:97], v[168:171], v[228:231], v[94:97]
	v_mfma_f32_16x16x32_bf16 v[90:93], v[180:183], v[228:231], v[90:93]
	v_mfma_f32_16x16x32_bf16 v[90:93], v[176:179], v[224:227], v[90:93]
	v_mfma_f32_16x16x32_bf16 v[74:77], v[176:179], v[232:235], v[74:77]
	v_mfma_f32_16x16x32_bf16 v[74:77], v[180:183], v[236:239], v[74:77]
	v_mfma_f32_16x16x32_bf16 v[78:81], v[168:171], v[236:239], v[78:81]
	v_mfma_f32_16x16x32_bf16 v[78:81], v[142:145], v[232:235], v[78:81]
	v_mfma_f32_16x16x32_bf16 v[70:73], v[184:187], v[232:235], v[70:73]
	v_mfma_f32_16x16x32_bf16 v[70:73], v[188:191], v[236:239], v[70:73]
	v_mfma_f32_16x16x32_bf16 v[66:69], v[204:207], v[236:239], v[66:69]
	v_mfma_f32_16x16x32_bf16 v[66:69], v[192:195], v[232:235], v[66:69]
	v_mfma_f32_16x16x32_bf16 v[82:85], v[192:195], v[224:227], v[82:85]
	v_mfma_f32_16x16x32_bf16 v[82:85], v[204:207], v[228:231], v[82:85]
	v_mfma_f32_16x16x32_bf16 v[86:89], v[188:191], v[228:231], v[86:89]
	v_mfma_f32_16x16x32_bf16 v[86:89], v[184:187], v[224:227], v[86:89]
	v_mfma_f32_16x16x32_bf16 v[102:105], v[184:187], v[216:219], v[102:105]
	v_mfma_f32_16x16x32_bf16 v[102:105], v[188:191], v[220:223], v[102:105]
	v_mfma_f32_16x16x32_bf16 v[98:101], v[204:207], v[220:223], v[98:101]
	v_mfma_f32_16x16x32_bf16 v[98:101], v[192:195], v[216:219], v[98:101]
	v_mfma_f32_16x16x32_bf16 v[114:117], v[192:195], v[208:211], v[114:117]
	v_mfma_f32_16x16x32_bf16 v[114:117], v[204:207], v[212:215], v[114:117]
	v_mfma_f32_16x16x32_bf16 v[118:121], v[188:191], v[212:215], v[118:121]
	v_mfma_f32_16x16x32_bf16 v[118:121], v[184:187], v[208:211], v[118:121]
	s_barrier
	s_mov_b32 m0, s48
	s_add_u32 s24, s24, 0x80
	s_addc_u32 s25, s25, 0
	global_load_lds_dwordx4 v132, s[24:25]
	s_mov_b32 m0, s49
	ds_read_b128 v[208:211], v158 offset:49152
	global_load_lds_dwordx4 v136, s[24:25]
	s_mov_b32 m0, s50
	s_add_u32 s24, s24, 0x2b0000
	s_addc_u32 s25, s25, 0
	global_load_lds_dwordx4 v132, s[24:25]
	s_add_i32 m0, s50, 0x2000
	ds_read_b128 v[212:215], v158 offset:50176
	global_load_lds_dwordx4 v136, s[24:25]
	ds_read_b128 v[216:219], v158 offset:51200
	ds_read_b128 v[220:223], v158 offset:52224
	ds_read_b128 v[224:227], v158 offset:53248
	ds_read_b128 v[228:231], v158 offset:54272
	ds_read_b128 v[232:235], v158 offset:55296
	ds_read_b128 v[236:239], v158 offset:56320
	s_waitcnt vmcnt(6)
	s_waitcnt lgkmcnt(0)
	s_barrier
	v_mfma_f32_16x16x32_bf16 v[62:65], v[142:145], v[208:211], v[62:65]
	v_mfma_f32_16x16x32_bf16 v[62:65], v[168:171], v[212:215], v[62:65]
	v_mfma_f32_16x16x32_bf16 v[58:61], v[180:183], v[212:215], v[58:61]
	v_mfma_f32_16x16x32_bf16 v[58:61], v[176:179], v[208:211], v[58:61]
	v_mfma_f32_16x16x32_bf16 v[42:45], v[176:179], v[216:219], v[42:45]
	v_mfma_f32_16x16x32_bf16 v[42:45], v[180:183], v[220:223], v[42:45]
	v_mfma_f32_16x16x32_bf16 v[46:49], v[168:171], v[220:223], v[46:49]
	v_mfma_f32_16x16x32_bf16 v[46:49], v[142:145], v[216:219], v[46:49]
	v_mfma_f32_16x16x32_bf16 v[30:33], v[142:145], v[224:227], v[30:33]
	v_mfma_f32_16x16x32_bf16 v[30:33], v[168:171], v[228:231], v[30:33]
	v_mfma_f32_16x16x32_bf16 v[26:29], v[180:183], v[228:231], v[26:29]
	v_mfma_f32_16x16x32_bf16 v[26:29], v[176:179], v[224:227], v[26:29]
	v_mfma_f32_16x16x32_bf16 v[10:13], v[176:179], v[232:235], v[10:13]
	v_mfma_f32_16x16x32_bf16 v[10:13], v[180:183], v[236:239], v[10:13]
	v_mfma_f32_16x16x32_bf16 v[14:17], v[168:171], v[236:239], v[14:17]
	v_mfma_f32_16x16x32_bf16 v[14:17], v[142:145], v[232:235], v[14:17]
	v_mfma_f32_16x16x32_bf16 v[6:9], v[184:187], v[232:235], v[6:9]
	v_mfma_f32_16x16x32_bf16 v[6:9], v[188:191], v[236:239], v[6:9]
	v_mfma_f32_16x16x32_bf16 v[2:5], v[204:207], v[236:239], v[2:5]
	v_mfma_f32_16x16x32_bf16 v[2:5], v[192:195], v[232:235], v[2:5]
	v_mfma_f32_16x16x32_bf16 v[18:21], v[192:195], v[224:227], v[18:21]
	v_mfma_f32_16x16x32_bf16 v[18:21], v[204:207], v[228:231], v[18:21]
	v_mfma_f32_16x16x32_bf16 v[22:25], v[188:191], v[228:231], v[22:25]
	v_mfma_f32_16x16x32_bf16 v[22:25], v[184:187], v[224:227], v[22:25]
	v_mfma_f32_16x16x32_bf16 v[38:41], v[184:187], v[216:219], v[38:41]
	v_mfma_f32_16x16x32_bf16 v[38:41], v[188:191], v[220:223], v[38:41]
	v_mfma_f32_16x16x32_bf16 v[34:37], v[204:207], v[220:223], v[34:37]
	v_mfma_f32_16x16x32_bf16 v[34:37], v[192:195], v[216:219], v[34:37]
	v_mfma_f32_16x16x32_bf16 v[50:53], v[192:195], v[208:211], v[50:53]
	v_mfma_f32_16x16x32_bf16 v[50:53], v[204:207], v[212:215], v[50:53]
	v_mfma_f32_16x16x32_bf16 v[54:57], v[188:191], v[212:215], v[54:57]
	v_mfma_f32_16x16x32_bf16 v[54:57], v[184:187], v[208:211], v[54:57]
	s_barrier
	s_add_i32 s55, s55, 2
	s_add_u32 s22, s22, 0x100
	s_addc_u32 s23, s23, 0
	s_add_u32 s53, s53, 0x100
	s_addc_u32 s54, s54, 0

.LBB0_1564:
	s_add_i32 s92, s92, 1
	s_mov_b32 s18, s12
	s_lshl_b32 s12, s92, 5
	s_add_i32 s12, s12, s3
	s_mov_b64 s[8:9], s[14:15]
	s_lshl_b32 s14, s12, 3
	s_ashr_i32 s13, s12, 2
	s_add_i32 s14, s14, s52
	s_cmpk_lt_i32 s12, 0x50
	s_cselect_b32 s12, s13, s14
	s_mov_b32 s40, s33
	s_cselect_b32 s33, s53, 32
	s_cmp_lt_i32 s12, 20
	s_cselect_b64 s[64:65], -1, 0
	s_lshl_b32 s13, s33, 21
	v_readlane_b32 s14, v250, 46
	s_mov_b64 s[6:7], s[16:17]
	v_readlane_b32 s15, v250, 47
	s_add_u32 s16, s14, s13
	s_addc_u32 s17, s15, 0
	s_and_b64 s[14:15], s[64:65], exec
	s_cselect_b32 s41, s17, s7
	s_cselect_b32 s50, s16, s6
	s_ashr_i32 s13, s12, 31
	s_lshl_b64 s[14:15], s[12:13], 21
	v_readlane_b32 s28, v250, 42
	v_readlane_b32 s29, v250, 43
	s_add_u32 s14, s28, s14
	s_addc_u32 s15, s29, s15
	s_and_b64 s[56:57], s[64:65], exec
	s_cselect_b32 s13, s15, s9
	s_cselect_b32 s51, s14, s8
	s_add_u32 s6, s6, 0x100080
	s_addc_u32 s7, s7, 0
	s_add_u32 s56, s8, 0x100
	s_addc_u32 s57, s9, 0
	s_mov_b32 s66, -2
	s_waitcnt lgkmcnt(0)
	ds_read_b128 v[130:133], v204
	ds_read_b128 v[134:137], v204 offset:1024
	ds_read_b128 v[138:141], v204 offset:2048
	ds_read_b128 v[142:145], v204 offset:3072
	ds_read_b128 v[146:149], v205
	ds_read_b128 v[150:153], v205 offset:1024
	ds_read_b128 v[154:157], v205 offset:2048
	ds_read_b128 v[158:161], v205 offset:3072
	s_add_u32 s8, s6, 0xfff00080
	s_addc_u32 s9, s7, -1
	s_cmp_eq_u32 s66, 60
	s_cselect_b32 s73, s41, s9
	s_cselect_b32 s72, s50, s8
	s_cselect_b32 s9, s13, s57
	s_cselect_b32 s8, s51, s56
	s_add_i32 m0, s42, 0xc000
	ds_read_b128 v[184:187], v206
	ds_read_b128 v[188:191], v206 offset:1024
	ds_read_b128 v[192:195], v206 offset:2048
	ds_read_b128 v[210:213], v206 offset:3072
	ds_read_b128 v[214:217], v206 offset:4096
	ds_read_b128 v[218:221], v206 offset:5120
	ds_read_b128 v[222:225], v206 offset:6144
	ds_read_b128 v[226:229], v206 offset:7168
	global_load_lds_dwordx4 v180, s[6:7]
	s_add_i32 m0, s42, 0xe000
	s_nop 0
	global_load_lds_dwordx4 v182, s[6:7]
	s_waitcnt vmcnt(8)
	s_waitcnt lgkmcnt(0)
	s_barrier
	v_mfma_f32_16x16x32_bf16 v[126:129], v[130:133], v[184:187], 0
	v_mfma_f32_16x16x32_bf16 v[126:129], v[134:137], v[188:191], v[126:129]
	v_mfma_f32_16x16x32_bf16 v[122:125], v[142:145], v[188:191], 0
	v_mfma_f32_16x16x32_bf16 v[122:125], v[138:141], v[184:187], v[122:125]
	v_mfma_f32_16x16x32_bf16 v[106:109], v[138:141], v[192:195], 0
	v_mfma_f32_16x16x32_bf16 v[106:109], v[142:145], v[210:213], v[106:109]
	v_mfma_f32_16x16x32_bf16 v[110:113], v[134:137], v[210:213], 0
	v_mfma_f32_16x16x32_bf16 v[110:113], v[130:133], v[192:195], v[110:113]
	v_mfma_f32_16x16x32_bf16 v[94:97], v[130:133], v[214:217], 0
	v_mfma_f32_16x16x32_bf16 v[94:97], v[134:137], v[218:221], v[94:97]
	v_mfma_f32_16x16x32_bf16 v[90:93], v[142:145], v[218:221], 0
	v_mfma_f32_16x16x32_bf16 v[90:93], v[138:141], v[214:217], v[90:93]
	v_mfma_f32_16x16x32_bf16 v[74:77], v[138:141], v[222:225], 0
	v_mfma_f32_16x16x32_bf16 v[74:77], v[142:145], v[226:229], v[74:77]
	v_mfma_f32_16x16x32_bf16 v[78:81], v[134:137], v[226:229], 0
	v_mfma_f32_16x16x32_bf16 v[78:81], v[130:133], v[222:225], v[78:81]
	v_mfma_f32_16x16x32_bf16 v[70:73], v[146:149], v[222:225], 0
	v_mfma_f32_16x16x32_bf16 v[70:73], v[150:153], v[226:229], v[70:73]
	v_mfma_f32_16x16x32_bf16 v[66:69], v[158:161], v[226:229], 0
	v_mfma_f32_16x16x32_bf16 v[66:69], v[154:157], v[222:225], v[66:69]
	v_mfma_f32_16x16x32_bf16 v[82:85], v[154:157], v[214:217], 0
	v_mfma_f32_16x16x32_bf16 v[82:85], v[158:161], v[218:221], v[82:85]
	v_mfma_f32_16x16x32_bf16 v[86:89], v[150:153], v[218:221], 0
	v_mfma_f32_16x16x32_bf16 v[86:89], v[146:149], v[214:217], v[86:89]
	v_mfma_f32_16x16x32_bf16 v[102:105], v[146:149], v[192:195], 0
	v_mfma_f32_16x16x32_bf16 v[102:105], v[150:153], v[210:213], v[102:105]
	v_mfma_f32_16x16x32_bf16 v[98:101], v[158:161], v[210:213], 0
	v_mfma_f32_16x16x32_bf16 v[98:101], v[154:157], v[192:195], v[98:101]
	v_mfma_f32_16x16x32_bf16 v[114:117], v[154:157], v[184:187], 0
	v_mfma_f32_16x16x32_bf16 v[114:117], v[158:161], v[188:191], v[114:117]
	v_mfma_f32_16x16x32_bf16 v[118:121], v[150:153], v[188:191], 0
	v_mfma_f32_16x16x32_bf16 v[118:121], v[146:149], v[184:187], v[118:121]
	s_barrier
	s_add_i32 s67, s54, s35
	s_mov_b32 m0, s67
	ds_read_b128 v[184:187], v206 offset:16384
	ds_read_b128 v[188:191], v206 offset:17408
	ds_read_b128 v[192:195], v206 offset:18432
	ds_read_b128 v[210:213], v206 offset:19456
	ds_read_b128 v[214:217], v206 offset:20480
	ds_read_b128 v[218:221], v206 offset:21504
	ds_read_b128 v[222:225], v206 offset:22528
	ds_read_b128 v[226:229], v206 offset:23552
	global_load_lds_dwordx4 v168, s[8:9]
	s_add_i32 m0, s67, 0x2000
	s_add_u32 s68, s8, 0x100000
	s_addc_u32 s69, s9, 0
	s_add_i32 s67, s55, s35
	global_load_lds_dwordx4 v170, s[8:9]
	s_mov_b32 m0, s67
	s_nop 0
	global_load_lds_dwordx4 v168, s[68:69]
	s_add_i32 m0, s67, 0x2000
	s_nop 0
	global_load_lds_dwordx4 v170, s[68:69]
	s_mov_b32 m0, s42
	s_nop 0
	global_load_lds_dwordx4 v168, s[72:73]
	s_mov_b32 m0, s43
	s_nop 0
	global_load_lds_dwordx4 v170, s[72:73]
	s_waitcnt vmcnt(8)
	s_waitcnt lgkmcnt(0)
	s_barrier
	v_mfma_f32_16x16x32_bf16 v[62:65], v[130:133], v[184:187], 0
	v_mfma_f32_16x16x32_bf16 v[62:65], v[134:137], v[188:191], v[62:65]
	v_mfma_f32_16x16x32_bf16 v[58:61], v[142:145], v[188:191], 0
	v_mfma_f32_16x16x32_bf16 v[58:61], v[138:141], v[184:187], v[58:61]
	v_mfma_f32_16x16x32_bf16 v[42:45], v[138:141], v[192:195], 0
	v_mfma_f32_16x16x32_bf16 v[42:45], v[142:145], v[210:213], v[42:45]
	v_mfma_f32_16x16x32_bf16 v[46:49], v[134:137], v[210:213], 0
	v_mfma_f32_16x16x32_bf16 v[46:49], v[130:133], v[192:195], v[46:49]
	v_mfma_f32_16x16x32_bf16 v[30:33], v[130:133], v[214:217], 0
	v_mfma_f32_16x16x32_bf16 v[30:33], v[134:137], v[218:221], v[30:33]
	v_mfma_f32_16x16x32_bf16 v[26:29], v[142:145], v[218:221], 0
	v_mfma_f32_16x16x32_bf16 v[26:29], v[138:141], v[214:217], v[26:29]
	v_mfma_f32_16x16x32_bf16 v[10:13], v[138:141], v[222:225], 0
	v_mfma_f32_16x16x32_bf16 v[10:13], v[142:145], v[226:229], v[10:13]
	v_mfma_f32_16x16x32_bf16 v[14:17], v[134:137], v[226:229], 0
	v_mfma_f32_16x16x32_bf16 v[14:17], v[130:133], v[222:225], v[14:17]
	v_mfma_f32_16x16x32_bf16 v[6:9], v[146:149], v[222:225], 0
	v_mfma_f32_16x16x32_bf16 v[6:9], v[150:153], v[226:229], v[6:9]
	v_mfma_f32_16x16x32_bf16 v[2:5], v[158:161], v[226:229], 0
	v_mfma_f32_16x16x32_bf16 v[2:5], v[154:157], v[222:225], v[2:5]
	v_mfma_f32_16x16x32_bf16 v[18:21], v[154:157], v[214:217], 0
	v_mfma_f32_16x16x32_bf16 v[18:21], v[158:161], v[218:221], v[18:21]
	v_mfma_f32_16x16x32_bf16 v[22:25], v[150:153], v[218:221], 0
	v_mfma_f32_16x16x32_bf16 v[22:25], v[146:149], v[214:217], v[22:25]
	v_mfma_f32_16x16x32_bf16 v[38:41], v[146:149], v[192:195], 0
	v_mfma_f32_16x16x32_bf16 v[38:41], v[150:153], v[210:213], v[38:41]
	v_mfma_f32_16x16x32_bf16 v[34:37], v[158:161], v[210:213], 0
	v_mfma_f32_16x16x32_bf16 v[34:37], v[154:157], v[192:195], v[34:37]
	v_mfma_f32_16x16x32_bf16 v[50:53], v[154:157], v[184:187], 0
	v_mfma_f32_16x16x32_bf16 v[50:53], v[158:161], v[188:191], v[50:53]
	v_mfma_f32_16x16x32_bf16 v[54:57], v[150:153], v[188:191], 0
	v_mfma_f32_16x16x32_bf16 v[54:57], v[146:149], v[184:187], v[54:57]
	s_barrier
	s_add_i32 s67, 0, 0x18000
	s_add_i32 s70, 0, 0x1c000
	v_add_u32_e32 v142, s67, v203
	v_add_u32_e32 v158, s70, v203
	ds_read_b128 v[130:133], v142
	ds_read_b128 v[134:137], v142 offset:1024
	ds_read_b128 v[138:141], v142 offset:2048
	ds_read_b128 v[142:145], v142 offset:3072
	ds_read_b128 v[146:149], v158
	ds_read_b128 v[150:153], v158 offset:1024
	ds_read_b128 v[154:157], v158 offset:2048
	ds_read_b128 v[158:161], v158 offset:3072
	s_add_u32 s68, s72, 0x100000
	s_addc_u32 s69, s73, 0
	s_mov_b32 m0, s44
	ds_read_b128 v[184:187], v206 offset:32768
	ds_read_b128 v[188:191], v206 offset:33792
	ds_read_b128 v[192:195], v206 offset:34816
	ds_read_b128 v[210:213], v206 offset:35840
	ds_read_b128 v[214:217], v206 offset:36864
	ds_read_b128 v[218:221], v206 offset:37888
	ds_read_b128 v[222:225], v206 offset:38912
	ds_read_b128 v[226:229], v206 offset:39936
	global_load_lds_dwordx4 v168, s[68:69]
	s_mov_b32 m0, s45
	s_nop 0
	global_load_lds_dwordx4 v170, s[68:69]
	s_waitcnt vmcnt(8)
	s_waitcnt lgkmcnt(0)
	s_barrier
	v_mfma_f32_16x16x32_bf16 v[126:129], v[130:133], v[184:187], v[126:129]
	v_mfma_f32_16x16x32_bf16 v[126:129], v[134:137], v[188:191], v[126:129]
	v_mfma_f32_16x16x32_bf16 v[122:125], v[142:145], v[188:191], v[122:125]
	v_mfma_f32_16x16x32_bf16 v[122:125], v[138:141], v[184:187], v[122:125]
	v_mfma_f32_16x16x32_bf16 v[106:109], v[138:141], v[192:195], v[106:109]
	v_mfma_f32_16x16x32_bf16 v[106:109], v[142:145], v[210:213], v[106:109]
	v_mfma_f32_16x16x32_bf16 v[110:113], v[134:137], v[210:213], v[110:113]
	v_mfma_f32_16x16x32_bf16 v[110:113], v[130:133], v[192:195], v[110:113]
	v_mfma_f32_16x16x32_bf16 v[94:97], v[130:133], v[214:217], v[94:97]
	v_mfma_f32_16x16x32_bf16 v[94:97], v[134:137], v[218:221], v[94:97]
	v_mfma_f32_16x16x32_bf16 v[90:93], v[142:145], v[218:221], v[90:93]
	v_mfma_f32_16x16x32_bf16 v[90:93], v[138:141], v[214:217], v[90:93]
	v_mfma_f32_16x16x32_bf16 v[74:77], v[138:141], v[222:225], v[74:77]
	v_mfma_f32_16x16x32_bf16 v[74:77], v[142:145], v[226:229], v[74:77]
	v_mfma_f32_16x16x32_bf16 v[78:81], v[134:137], v[226:229], v[78:81]
	v_mfma_f32_16x16x32_bf16 v[78:81], v[130:133], v[222:225], v[78:81]
	v_mfma_f32_16x16x32_bf16 v[70:73], v[146:149], v[222:225], v[70:73]
	v_mfma_f32_16x16x32_bf16 v[70:73], v[150:153], v[226:229], v[70:73]
	v_mfma_f32_16x16x32_bf16 v[66:69], v[158:161], v[226:229], v[66:69]
	v_mfma_f32_16x16x32_bf16 v[66:69], v[154:157], v[222:225], v[66:69]
	v_mfma_f32_16x16x32_bf16 v[82:85], v[154:157], v[214:217], v[82:85]
	v_mfma_f32_16x16x32_bf16 v[82:85], v[158:161], v[218:221], v[82:85]
	v_mfma_f32_16x16x32_bf16 v[86:89], v[150:153], v[218:221], v[86:89]
	v_mfma_f32_16x16x32_bf16 v[86:89], v[146:149], v[214:217], v[86:89]
	v_mfma_f32_16x16x32_bf16 v[102:105], v[146:149], v[192:195], v[102:105]
	v_mfma_f32_16x16x32_bf16 v[102:105], v[150:153], v[210:213], v[102:105]
	v_mfma_f32_16x16x32_bf16 v[98:101], v[158:161], v[210:213], v[98:101]
	v_mfma_f32_16x16x32_bf16 v[98:101], v[154:157], v[192:195], v[98:101]
	v_mfma_f32_16x16x32_bf16 v[114:117], v[154:157], v[184:187], v[114:117]
	v_mfma_f32_16x16x32_bf16 v[114:117], v[158:161], v[188:191], v[114:117]
	v_mfma_f32_16x16x32_bf16 v[118:121], v[150:153], v[188:191], v[118:121]
	v_mfma_f32_16x16x32_bf16 v[118:121], v[146:149], v[184:187], v[118:121]
	s_barrier
	s_add_u32 s68, s72, 0x80
	s_addc_u32 s69, s73, 0
	s_add_u32 s8, s8, 0x80
	s_addc_u32 s9, s9, 0
	s_add_i32 s67, s67, s35
	s_mov_b32 m0, s67
	ds_read_b128 v[184:187], v206 offset:49152
	ds_read_b128 v[188:191], v206 offset:50176
	ds_read_b128 v[192:195], v206 offset:51200
	ds_read_b128 v[210:213], v206 offset:52224
	ds_read_b128 v[214:217], v206 offset:53248
	ds_read_b128 v[218:221], v206 offset:54272
	ds_read_b128 v[222:225], v206 offset:55296
	ds_read_b128 v[226:229], v206 offset:56320
	global_load_lds_dwordx4 v168, s[8:9]
	s_add_i32 m0, s67, 0x2000
	s_add_i32 s67, s70, s35
	global_load_lds_dwordx4 v170, s[8:9]
	s_add_u32 s8, s8, 0x100000
	s_addc_u32 s9, s9, 0
	s_mov_b32 m0, s67
	s_nop 0
	global_load_lds_dwordx4 v168, s[8:9]
	s_add_i32 m0, s67, 0x2000
	s_nop 0
	global_load_lds_dwordx4 v170, s[8:9]
	s_mov_b32 m0, s48
	s_nop 0
	global_load_lds_dwordx4 v168, s[68:69]
	s_mov_b32 m0, s49
	s_nop 0
	global_load_lds_dwordx4 v170, s[68:69]
	s_waitcnt vmcnt(8)
	s_waitcnt lgkmcnt(0)
	s_barrier
	v_mfma_f32_16x16x32_bf16 v[62:65], v[130:133], v[184:187], v[62:65]
	v_mfma_f32_16x16x32_bf16 v[62:65], v[134:137], v[188:191], v[62:65]
	v_mfma_f32_16x16x32_bf16 v[58:61], v[142:145], v[188:191], v[58:61]
	v_mfma_f32_16x16x32_bf16 v[58:61], v[138:141], v[184:187], v[58:61]
	v_mfma_f32_16x16x32_bf16 v[42:45], v[138:141], v[192:195], v[42:45]
	v_mfma_f32_16x16x32_bf16 v[42:45], v[142:145], v[210:213], v[42:45]
	v_mfma_f32_16x16x32_bf16 v[46:49], v[134:137], v[210:213], v[46:49]
	v_mfma_f32_16x16x32_bf16 v[46:49], v[130:133], v[192:195], v[46:49]
	v_mfma_f32_16x16x32_bf16 v[30:33], v[130:133], v[214:217], v[30:33]
	v_mfma_f32_16x16x32_bf16 v[30:33], v[134:137], v[218:221], v[30:33]
	v_mfma_f32_16x16x32_bf16 v[26:29], v[142:145], v[218:221], v[26:29]
	v_mfma_f32_16x16x32_bf16 v[26:29], v[138:141], v[214:217], v[26:29]
	v_mfma_f32_16x16x32_bf16 v[10:13], v[138:141], v[222:225], v[10:13]
	v_mfma_f32_16x16x32_bf16 v[10:13], v[142:145], v[226:229], v[10:13]
	v_mfma_f32_16x16x32_bf16 v[14:17], v[134:137], v[226:229], v[14:17]
	v_mfma_f32_16x16x32_bf16 v[14:17], v[130:133], v[222:225], v[14:17]
	v_mfma_f32_16x16x32_bf16 v[6:9], v[146:149], v[222:225], v[6:9]
	v_mfma_f32_16x16x32_bf16 v[6:9], v[150:153], v[226:229], v[6:9]
	v_mfma_f32_16x16x32_bf16 v[2:5], v[158:161], v[226:229], v[2:5]
	v_mfma_f32_16x16x32_bf16 v[2:5], v[154:157], v[222:225], v[2:5]
	v_mfma_f32_16x16x32_bf16 v[18:21], v[154:157], v[214:217], v[18:21]
	v_mfma_f32_16x16x32_bf16 v[18:21], v[158:161], v[218:221], v[18:21]
	v_mfma_f32_16x16x32_bf16 v[22:25], v[150:153], v[218:221], v[22:25]
	v_mfma_f32_16x16x32_bf16 v[22:25], v[146:149], v[214:217], v[22:25]
	v_mfma_f32_16x16x32_bf16 v[38:41], v[146:149], v[192:195], v[38:41]
	v_mfma_f32_16x16x32_bf16 v[38:41], v[150:153], v[210:213], v[38:41]
	v_mfma_f32_16x16x32_bf16 v[34:37], v[158:161], v[210:213], v[34:37]
	v_mfma_f32_16x16x32_bf16 v[34:37], v[154:157], v[192:195], v[34:37]
	v_mfma_f32_16x16x32_bf16 v[50:53], v[154:157], v[184:187], v[50:53]
	v_mfma_f32_16x16x32_bf16 v[50:53], v[158:161], v[188:191], v[50:53]
	v_mfma_f32_16x16x32_bf16 v[54:57], v[150:153], v[188:191], v[54:57]
	v_mfma_f32_16x16x32_bf16 v[54:57], v[146:149], v[184:187], v[54:57]
	s_barrier
	s_add_i32 s66, s66, 2
	s_add_u32 s6, s6, 0x100
	s_addc_u32 s7, s7, 0
	s_add_u32 s56, s56, 0x100
	s_addc_u32 s57, s57, 0

.LBB0_2229:
	s_add_i32 s35, s35, 1
	s_lshl_b32 s7, s35, 5
	s_add_i32 s7, s7, s3
	s_ashr_i32 s19, s7, 2
	s_cmp_lt_i32 s19, 16
	s_mov_b64 s[24:25], s[8:9]
	s_cselect_b64 s[8:9], -1, 0
	s_cmp_lt_i32 s7, 64
	s_mov_b64 s[22:23], s[10:11]
	s_cselect_b64 s[10:11], -1, 0
	s_and_b64 s[20:21], s[10:11], exec
	s_mov_b32 s43, s18
	s_cselect_b32 s18, s29, s18
	s_mov_b32 s42, s6
	s_cselect_b32 s6, s19, s6
	s_ashr_i32 s19, s18, 31
	s_and_b64 s[20:21], s[10:11], s[8:9]
	s_lshl_b64 s[8:9], s[18:19], 21
	v_readlane_b32 s0, v250, 46
	v_readlane_b32 s1, v250, 47
	s_add_u32 s10, s0, s8
	s_addc_u32 s11, s1, s9
	s_and_b64 s[8:9], s[20:21], exec
	s_cselect_b32 s19, s11, s23
	s_cselect_b32 s44, s10, s22
	s_ashr_i32 s7, s6, 31
	s_lshl_b64 s[8:9], s[6:7], 21
	v_readlane_b32 s0, v250, 44
	v_readlane_b32 s1, v250, 45
	s_add_u32 s8, s0, s8
	s_addc_u32 s9, s1, s9
	s_and_b64 s[26:27], s[20:21], exec
	s_cselect_b32 s7, s9, s25
	s_cselect_b32 s45, s8, s24
	s_add_u32 s22, s22, 0x100080
	s_addc_u32 s23, s23, 0
	s_add_u32 s46, s24, 0x100
	s_addc_u32 s47, s25, 0
	s_mov_b32 s48, -2
	s_waitcnt lgkmcnt(0)
	ds_read_b128 v[142:145], v154
	ds_read_b128 v[158:161], v154 offset:1024
	ds_read_b128 v[168:171], v154 offset:2048
	ds_read_b128 v[176:179], v154 offset:3072
	ds_read_b128 v[180:183], v155
	ds_read_b128 v[184:187], v155 offset:1024
	ds_read_b128 v[188:191], v155 offset:2048
	ds_read_b128 v[192:195], v155 offset:3072
	s_add_u32 s24, s22, 0xfff00080
	s_addc_u32 s25, s23, -1
	s_cmp_eq_u32 s48, 60
	s_cselect_b32 s27, s19, s25
	s_cselect_b32 s26, s44, s24
	s_cselect_b32 s25, s7, s47
	s_cselect_b32 s24, s45, s46
	s_mov_b32 m0, s40
	ds_read_b128 v[204:207], v156
	ds_read_b128 v[208:211], v156 offset:1024
	ds_read_b128 v[212:215], v156 offset:2048
	ds_read_b128 v[216:219], v156 offset:3072
	ds_read_b128 v[220:223], v156 offset:4096
	ds_read_b128 v[224:227], v156 offset:5120
	ds_read_b128 v[228:231], v156 offset:6144
	ds_read_b128 v[232:235], v156 offset:7168
	global_load_lds_dwordx4 v138, s[22:23]
	s_mov_b32 m0, s41
	s_nop 0
	global_load_lds_dwordx4 v140, s[22:23]
	s_waitcnt vmcnt(8)
	s_waitcnt lgkmcnt(0)
	s_barrier
	v_mfma_f32_16x16x32_bf16 v[126:129], v[142:145], v[204:207], 0
	v_mfma_f32_16x16x32_bf16 v[126:129], v[158:161], v[208:211], v[126:129]
	v_mfma_f32_16x16x32_bf16 v[122:125], v[176:179], v[208:211], 0
	v_mfma_f32_16x16x32_bf16 v[122:125], v[168:171], v[204:207], v[122:125]
	v_mfma_f32_16x16x32_bf16 v[106:109], v[168:171], v[212:215], 0
	v_mfma_f32_16x16x32_bf16 v[106:109], v[176:179], v[216:219], v[106:109]
	v_mfma_f32_16x16x32_bf16 v[110:113], v[158:161], v[216:219], 0
	v_mfma_f32_16x16x32_bf16 v[110:113], v[142:145], v[212:215], v[110:113]
	v_mfma_f32_16x16x32_bf16 v[94:97], v[142:145], v[220:223], 0
	v_mfma_f32_16x16x32_bf16 v[94:97], v[158:161], v[224:227], v[94:97]
	v_mfma_f32_16x16x32_bf16 v[90:93], v[176:179], v[224:227], 0
	v_mfma_f32_16x16x32_bf16 v[90:93], v[168:171], v[220:223], v[90:93]
	v_mfma_f32_16x16x32_bf16 v[74:77], v[168:171], v[228:231], 0
	v_mfma_f32_16x16x32_bf16 v[74:77], v[176:179], v[232:235], v[74:77]
	v_mfma_f32_16x16x32_bf16 v[78:81], v[158:161], v[232:235], 0
	v_mfma_f32_16x16x32_bf16 v[78:81], v[142:145], v[228:231], v[78:81]
	v_mfma_f32_16x16x32_bf16 v[70:73], v[180:183], v[228:231], 0
	v_mfma_f32_16x16x32_bf16 v[70:73], v[184:187], v[232:235], v[70:73]
	v_mfma_f32_16x16x32_bf16 v[66:69], v[192:195], v[232:235], 0
	v_mfma_f32_16x16x32_bf16 v[66:69], v[188:191], v[228:231], v[66:69]
	v_mfma_f32_16x16x32_bf16 v[82:85], v[188:191], v[220:223], 0
	v_mfma_f32_16x16x32_bf16 v[82:85], v[192:195], v[224:227], v[82:85]
	v_mfma_f32_16x16x32_bf16 v[86:89], v[184:187], v[224:227], 0
	v_mfma_f32_16x16x32_bf16 v[86:89], v[180:183], v[220:223], v[86:89]
	v_mfma_f32_16x16x32_bf16 v[102:105], v[180:183], v[212:215], 0
	v_mfma_f32_16x16x32_bf16 v[102:105], v[184:187], v[216:219], v[102:105]
	v_mfma_f32_16x16x32_bf16 v[98:101], v[192:195], v[216:219], 0
	v_mfma_f32_16x16x32_bf16 v[98:101], v[188:191], v[212:215], v[98:101]
	v_mfma_f32_16x16x32_bf16 v[114:117], v[188:191], v[204:207], 0
	v_mfma_f32_16x16x32_bf16 v[114:117], v[192:195], v[208:211], v[114:117]
	v_mfma_f32_16x16x32_bf16 v[118:121], v[184:187], v[208:211], 0
	v_mfma_f32_16x16x32_bf16 v[118:121], v[180:183], v[204:207], v[118:121]
	s_barrier
	s_add_i32 s49, s38, s28
	s_mov_b32 m0, s49
	ds_read_b128 v[204:207], v156 offset:16384
	ds_read_b128 v[208:211], v156 offset:17408
	ds_read_b128 v[212:215], v156 offset:18432
	ds_read_b128 v[216:219], v156 offset:19456
	ds_read_b128 v[220:223], v156 offset:20480
	ds_read_b128 v[224:227], v156 offset:21504
	ds_read_b128 v[228:231], v156 offset:22528
	ds_read_b128 v[232:235], v156 offset:23552
	global_load_lds_dwordx4 v132, s[24:25]
	s_add_i32 m0, s49, 0x2000
	s_add_u32 s50, s24, 0x100000
	s_addc_u32 s51, s25, 0
	s_add_i32 s49, s39, s28
	global_load_lds_dwordx4 v136, s[24:25]
	s_mov_b32 m0, s49
	s_nop 0
	global_load_lds_dwordx4 v132, s[50:51]
	s_add_i32 m0, s49, 0x2000
	s_nop 0
	global_load_lds_dwordx4 v136, s[50:51]
	s_mov_b32 m0, s30
	s_nop 0
	global_load_lds_dwordx4 v130, s[26:27]
	s_mov_b32 m0, s31
	s_nop 0
	global_load_lds_dwordx4 v134, s[26:27]
	s_waitcnt vmcnt(8)
	s_waitcnt lgkmcnt(0)
	s_barrier
	v_mfma_f32_16x16x32_bf16 v[62:65], v[142:145], v[204:207], 0
	v_mfma_f32_16x16x32_bf16 v[62:65], v[158:161], v[208:211], v[62:65]
	v_mfma_f32_16x16x32_bf16 v[58:61], v[176:179], v[208:211], 0
	v_mfma_f32_16x16x32_bf16 v[58:61], v[168:171], v[204:207], v[58:61]
	v_mfma_f32_16x16x32_bf16 v[42:45], v[168:171], v[212:215], 0
	v_mfma_f32_16x16x32_bf16 v[42:45], v[176:179], v[216:219], v[42:45]
	v_mfma_f32_16x16x32_bf16 v[46:49], v[158:161], v[216:219], 0
	v_mfma_f32_16x16x32_bf16 v[46:49], v[142:145], v[212:215], v[46:49]
	v_mfma_f32_16x16x32_bf16 v[30:33], v[142:145], v[220:223], 0
	v_mfma_f32_16x16x32_bf16 v[30:33], v[158:161], v[224:227], v[30:33]
	v_mfma_f32_16x16x32_bf16 v[26:29], v[176:179], v[224:227], 0
	v_mfma_f32_16x16x32_bf16 v[26:29], v[168:171], v[220:223], v[26:29]
	v_mfma_f32_16x16x32_bf16 v[10:13], v[168:171], v[228:231], 0
	v_mfma_f32_16x16x32_bf16 v[10:13], v[176:179], v[232:235], v[10:13]
	v_mfma_f32_16x16x32_bf16 v[14:17], v[158:161], v[232:235], 0
	v_mfma_f32_16x16x32_bf16 v[14:17], v[142:145], v[228:231], v[14:17]
	v_mfma_f32_16x16x32_bf16 v[6:9], v[180:183], v[228:231], 0
	v_mfma_f32_16x16x32_bf16 v[6:9], v[184:187], v[232:235], v[6:9]
	v_mfma_f32_16x16x32_bf16 v[2:5], v[192:195], v[232:235], 0
	v_mfma_f32_16x16x32_bf16 v[2:5], v[188:191], v[228:231], v[2:5]
	v_mfma_f32_16x16x32_bf16 v[18:21], v[188:191], v[220:223], 0
	v_mfma_f32_16x16x32_bf16 v[18:21], v[192:195], v[224:227], v[18:21]
	v_mfma_f32_16x16x32_bf16 v[22:25], v[184:187], v[224:227], 0
	v_mfma_f32_16x16x32_bf16 v[22:25], v[180:183], v[220:223], v[22:25]
	v_mfma_f32_16x16x32_bf16 v[38:41], v[180:183], v[212:215], 0
	v_mfma_f32_16x16x32_bf16 v[38:41], v[184:187], v[216:219], v[38:41]
	v_mfma_f32_16x16x32_bf16 v[34:37], v[192:195], v[216:219], 0
	v_mfma_f32_16x16x32_bf16 v[34:37], v[188:191], v[212:215], v[34:37]
	v_mfma_f32_16x16x32_bf16 v[50:53], v[188:191], v[204:207], 0
	v_mfma_f32_16x16x32_bf16 v[50:53], v[192:195], v[208:211], v[50:53]
	v_mfma_f32_16x16x32_bf16 v[54:57], v[184:187], v[208:211], 0
	v_mfma_f32_16x16x32_bf16 v[54:57], v[180:183], v[204:207], v[54:57]
	s_barrier
	s_add_i32 s49, 0, 0x18000
	v_add_u32_e32 v157, s49, v152
	s_add_i32 s50, 0, 0x1c000
	ds_read_b128 v[142:145], v157
	ds_read_b128 v[158:161], v157 offset:1024
	ds_read_b128 v[168:171], v157 offset:2048
	ds_read_b128 v[176:179], v157 offset:3072
	v_add_u32_e32 v157, s50, v152
	ds_read_b128 v[180:183], v157
	ds_read_b128 v[184:187], v157 offset:1024
	ds_read_b128 v[188:191], v157 offset:2048
	ds_read_b128 v[192:195], v157 offset:3072
	s_add_u32 s26, s26, 0x100000
	s_addc_u32 s27, s27, 0
	s_mov_b32 m0, s33
	ds_read_b128 v[204:207], v156 offset:32768
	ds_read_b128 v[208:211], v156 offset:33792
	ds_read_b128 v[212:215], v156 offset:34816
	ds_read_b128 v[216:219], v156 offset:35840
	ds_read_b128 v[220:223], v156 offset:36864
	ds_read_b128 v[224:227], v156 offset:37888
	ds_read_b128 v[228:231], v156 offset:38912
	ds_read_b128 v[232:235], v156 offset:39936
	global_load_lds_dwordx4 v130, s[26:27]
	s_mov_b32 m0, s34
	s_nop 0
	global_load_lds_dwordx4 v134, s[26:27]
	s_waitcnt vmcnt(8)
	s_waitcnt lgkmcnt(0)
	s_barrier
	v_mfma_f32_16x16x32_bf16 v[126:129], v[142:145], v[204:207], v[126:129]
	v_mfma_f32_16x16x32_bf16 v[126:129], v[158:161], v[208:211], v[126:129]
	v_mfma_f32_16x16x32_bf16 v[122:125], v[176:179], v[208:211], v[122:125]
	v_mfma_f32_16x16x32_bf16 v[122:125], v[168:171], v[204:207], v[122:125]
	v_mfma_f32_16x16x32_bf16 v[106:109], v[168:171], v[212:215], v[106:109]
	v_mfma_f32_16x16x32_bf16 v[106:109], v[176:179], v[216:219], v[106:109]
	v_mfma_f32_16x16x32_bf16 v[110:113], v[158:161], v[216:219], v[110:113]
	v_mfma_f32_16x16x32_bf16 v[110:113], v[142:145], v[212:215], v[110:113]
	v_mfma_f32_16x16x32_bf16 v[94:97], v[142:145], v[220:223], v[94:97]
	v_mfma_f32_16x16x32_bf16 v[94:97], v[158:161], v[224:227], v[94:97]
	v_mfma_f32_16x16x32_bf16 v[90:93], v[176:179], v[224:227], v[90:93]
	v_mfma_f32_16x16x32_bf16 v[90:93], v[168:171], v[220:223], v[90:93]
	v_mfma_f32_16x16x32_bf16 v[74:77], v[168:171], v[228:231], v[74:77]
	v_mfma_f32_16x16x32_bf16 v[74:77], v[176:179], v[232:235], v[74:77]
	v_mfma_f32_16x16x32_bf16 v[78:81], v[158:161], v[232:235], v[78:81]
	v_mfma_f32_16x16x32_bf16 v[78:81], v[142:145], v[228:231], v[78:81]
	v_mfma_f32_16x16x32_bf16 v[70:73], v[180:183], v[228:231], v[70:73]
	v_mfma_f32_16x16x32_bf16 v[70:73], v[184:187], v[232:235], v[70:73]
	v_mfma_f32_16x16x32_bf16 v[66:69], v[192:195], v[232:235], v[66:69]
	v_mfma_f32_16x16x32_bf16 v[66:69], v[188:191], v[228:231], v[66:69]
	v_mfma_f32_16x16x32_bf16 v[82:85], v[188:191], v[220:223], v[82:85]
	v_mfma_f32_16x16x32_bf16 v[82:85], v[192:195], v[224:227], v[82:85]
	v_mfma_f32_16x16x32_bf16 v[86:89], v[184:187], v[224:227], v[86:89]
	v_mfma_f32_16x16x32_bf16 v[86:89], v[180:183], v[220:223], v[86:89]
	v_mfma_f32_16x16x32_bf16 v[102:105], v[180:183], v[212:215], v[102:105]
	v_mfma_f32_16x16x32_bf16 v[102:105], v[184:187], v[216:219], v[102:105]
	v_mfma_f32_16x16x32_bf16 v[98:101], v[192:195], v[216:219], v[98:101]
	v_mfma_f32_16x16x32_bf16 v[98:101], v[188:191], v[212:215], v[98:101]
	v_mfma_f32_16x16x32_bf16 v[114:117], v[188:191], v[204:207], v[114:117]
	v_mfma_f32_16x16x32_bf16 v[114:117], v[192:195], v[208:211], v[114:117]
	v_mfma_f32_16x16x32_bf16 v[118:121], v[184:187], v[208:211], v[118:121]
	v_mfma_f32_16x16x32_bf16 v[118:121], v[180:183], v[204:207], v[118:121]
	s_barrier
	s_add_u32 s98, s26, 0xfff00080
	s_addc_u32 s99, s27, -1
	s_add_u32 s24, s24, 0x80
	s_addc_u32 s25, s25, 0
	s_add_i32 s26, s49, s28
	s_mov_b32 m0, s26
	ds_read_b128 v[204:207], v156 offset:49152
	ds_read_b128 v[208:211], v156 offset:50176
	ds_read_b128 v[212:215], v156 offset:51200
	ds_read_b128 v[216:219], v156 offset:52224
	ds_read_b128 v[220:223], v156 offset:53248
	ds_read_b128 v[224:227], v156 offset:54272
	ds_read_b128 v[228:231], v156 offset:55296
	ds_read_b128 v[232:235], v156 offset:56320
	global_load_lds_dwordx4 v132, s[24:25]
	s_add_i32 m0, s26, 0x2000
	s_add_i32 s26, s50, s28
	global_load_lds_dwordx4 v136, s[24:25]
	s_add_u32 s24, s24, 0x100000
	s_addc_u32 s25, s25, 0
	s_mov_b32 m0, s26
	s_nop 0
	global_load_lds_dwordx4 v132, s[24:25]
	s_add_i32 m0, s26, 0x2000
	s_nop 0
	global_load_lds_dwordx4 v136, s[24:25]
	s_mov_b32 m0, s36
	s_nop 0
	global_load_lds_dwordx4 v130, s[98:99]
	s_mov_b32 m0, s37
	s_nop 0
	global_load_lds_dwordx4 v134, s[98:99]
	s_waitcnt vmcnt(8)
	s_waitcnt lgkmcnt(0)
	s_barrier
	v_mfma_f32_16x16x32_bf16 v[62:65], v[142:145], v[204:207], v[62:65]
	v_mfma_f32_16x16x32_bf16 v[62:65], v[158:161], v[208:211], v[62:65]
	v_mfma_f32_16x16x32_bf16 v[58:61], v[176:179], v[208:211], v[58:61]
	v_mfma_f32_16x16x32_bf16 v[58:61], v[168:171], v[204:207], v[58:61]
	v_mfma_f32_16x16x32_bf16 v[42:45], v[168:171], v[212:215], v[42:45]
	v_mfma_f32_16x16x32_bf16 v[42:45], v[176:179], v[216:219], v[42:45]
	v_mfma_f32_16x16x32_bf16 v[46:49], v[158:161], v[216:219], v[46:49]
	v_mfma_f32_16x16x32_bf16 v[46:49], v[142:145], v[212:215], v[46:49]
	v_mfma_f32_16x16x32_bf16 v[30:33], v[142:145], v[220:223], v[30:33]
	v_mfma_f32_16x16x32_bf16 v[30:33], v[158:161], v[224:227], v[30:33]
	v_mfma_f32_16x16x32_bf16 v[26:29], v[176:179], v[224:227], v[26:29]
	v_mfma_f32_16x16x32_bf16 v[26:29], v[168:171], v[220:223], v[26:29]
	v_mfma_f32_16x16x32_bf16 v[10:13], v[168:171], v[228:231], v[10:13]
	v_mfma_f32_16x16x32_bf16 v[10:13], v[176:179], v[232:235], v[10:13]
	v_mfma_f32_16x16x32_bf16 v[14:17], v[158:161], v[232:235], v[14:17]
	v_mfma_f32_16x16x32_bf16 v[14:17], v[142:145], v[228:231], v[14:17]
	v_mfma_f32_16x16x32_bf16 v[6:9], v[180:183], v[228:231], v[6:9]
	v_mfma_f32_16x16x32_bf16 v[6:9], v[184:187], v[232:235], v[6:9]
	v_mfma_f32_16x16x32_bf16 v[2:5], v[192:195], v[232:235], v[2:5]
	v_mfma_f32_16x16x32_bf16 v[2:5], v[188:191], v[228:231], v[2:5]
	v_mfma_f32_16x16x32_bf16 v[18:21], v[188:191], v[220:223], v[18:21]
	v_mfma_f32_16x16x32_bf16 v[18:21], v[192:195], v[224:227], v[18:21]
	v_mfma_f32_16x16x32_bf16 v[22:25], v[184:187], v[224:227], v[22:25]
	v_mfma_f32_16x16x32_bf16 v[22:25], v[180:183], v[220:223], v[22:25]
	v_mfma_f32_16x16x32_bf16 v[38:41], v[180:183], v[212:215], v[38:41]
	v_mfma_f32_16x16x32_bf16 v[38:41], v[184:187], v[216:219], v[38:41]
	v_mfma_f32_16x16x32_bf16 v[34:37], v[192:195], v[216:219], v[34:37]
	v_mfma_f32_16x16x32_bf16 v[34:37], v[188:191], v[212:215], v[34:37]
	v_mfma_f32_16x16x32_bf16 v[50:53], v[188:191], v[204:207], v[50:53]
	v_mfma_f32_16x16x32_bf16 v[50:53], v[192:195], v[208:211], v[50:53]
	v_mfma_f32_16x16x32_bf16 v[54:57], v[184:187], v[208:211], v[54:57]
	v_mfma_f32_16x16x32_bf16 v[54:57], v[180:183], v[204:207], v[54:57]
	s_barrier
	s_add_i32 s48, s48, 2
	s_add_u32 s22, s22, 0x100
	s_addc_u32 s23, s23, 0
	s_add_u32 s46, s46, 0x100
	s_addc_u32 s47, s47, 0

.LBB0_2372:
	s_add_i32 s34, s34, 1
	s_mov_b32 s50, s6
	s_lshl_b32 s6, s34, 5
	s_add_i32 s6, s6, s3
	s_mov_b64 s[22:23], s[8:9]
	s_lshl_b32 s8, s6, 3
	s_ashr_i32 s7, s6, 2
	s_add_i32 s8, s8, s37
	s_cmpk_lt_i32 s6, 0x158
	s_cselect_b32 s6, s7, s8
	s_mov_b32 s51, s26
	s_cselect_b32 s26, s38, 32
	s_cmpk_lt_i32 s6, 0x56
	s_cselect_b64 s[18:19], -1, 0
	s_lshl_b32 s7, s26, 21
	v_readlane_b32 s0, v250, 46
	s_mov_b64 s[20:21], s[10:11]
	v_readlane_b32 s1, v250, 47
	s_add_u32 s10, s0, s7
	s_addc_u32 s11, s1, 0
	s_and_b64 s[8:9], s[18:19], exec
	s_cselect_b32 s52, s11, s21
	s_cselect_b32 s53, s10, s20
	s_ashr_i32 s7, s6, 31
	s_lshl_b64 s[8:9], s[6:7], 21
	s_add_u32 s8, s27, s8
	s_addc_u32 s9, s28, s9
	s_and_b64 s[24:25], s[18:19], exec
	s_cselect_b32 s7, s9, s23
	s_cselect_b32 s54, s8, s22
	s_add_u32 s20, s20, 0x100080
	s_addc_u32 s21, s21, 0
	s_add_u32 s55, s22, 0x100
	s_addc_u32 s56, s23, 0
	s_mov_b32 s57, -2
	s_waitcnt lgkmcnt(0)
	s_add_u32 s60, s20, 0xfff00000
	s_addc_u32 s61, s21, -1
	s_mov_b32 m0, s35
	ds_read_b128 v[142:145], v148
	global_load_lds_dwordx4 v130, s[60:61]
	s_mov_b32 m0, s36
	ds_read_b128 v[154:157], v148 offset:1024
	global_load_lds_dwordx4 v134, s[60:61]
	s_mov_b32 m0, s40
	ds_read_b128 v[158:161], v148 offset:2048
	global_load_lds_dwordx4 v138, s[20:21]
	s_mov_b32 m0, s41
	ds_read_b128 v[168:171], v148 offset:3072
	global_load_lds_dwordx4 v140, s[20:21]
	ds_read_b128 v[176:179], v149
	ds_read_b128 v[180:183], v149 offset:1024
	ds_read_b128 v[184:187], v149 offset:2048
	ds_read_b128 v[188:191], v149 offset:3072
	s_add_u32 s22, s20, 0xfff00080
	s_addc_u32 s23, s21, -1
	s_cmp_eq_u32 s57, 60
	s_cselect_b32 s25, s52, s23
	s_cselect_b32 s24, s53, s22
	s_cselect_b32 s23, s7, s56
	s_cselect_b32 s22, s54, s55
	ds_read_b128 v[192:195], v150
	ds_read_b128 v[204:207], v150 offset:1024
	ds_read_b128 v[208:211], v150 offset:2048
	ds_read_b128 v[212:215], v150 offset:3072
	ds_read_b128 v[216:219], v150 offset:4096
	ds_read_b128 v[220:223], v150 offset:5120
	ds_read_b128 v[224:227], v150 offset:6144
	ds_read_b128 v[228:231], v150 offset:7168
	s_waitcnt vmcnt(8)
	s_waitcnt lgkmcnt(0)
	s_barrier
	v_mfma_f32_16x16x32_bf16 v[126:129], v[142:145], v[192:195], 0
	v_mfma_f32_16x16x32_bf16 v[126:129], v[154:157], v[204:207], v[126:129]
	v_mfma_f32_16x16x32_bf16 v[122:125], v[168:171], v[204:207], 0
	v_mfma_f32_16x16x32_bf16 v[122:125], v[158:161], v[192:195], v[122:125]
	v_mfma_f32_16x16x32_bf16 v[106:109], v[158:161], v[208:211], 0
	v_mfma_f32_16x16x32_bf16 v[106:109], v[168:171], v[212:215], v[106:109]
	v_mfma_f32_16x16x32_bf16 v[110:113], v[154:157], v[212:215], 0
	v_mfma_f32_16x16x32_bf16 v[110:113], v[142:145], v[208:211], v[110:113]
	v_mfma_f32_16x16x32_bf16 v[94:97], v[142:145], v[216:219], 0
	v_mfma_f32_16x16x32_bf16 v[94:97], v[154:157], v[220:223], v[94:97]
	v_mfma_f32_16x16x32_bf16 v[90:93], v[168:171], v[220:223], 0
	v_mfma_f32_16x16x32_bf16 v[90:93], v[158:161], v[216:219], v[90:93]
	v_mfma_f32_16x16x32_bf16 v[74:77], v[158:161], v[224:227], 0
	v_mfma_f32_16x16x32_bf16 v[74:77], v[168:171], v[228:231], v[74:77]
	v_mfma_f32_16x16x32_bf16 v[78:81], v[154:157], v[228:231], 0
	v_mfma_f32_16x16x32_bf16 v[78:81], v[142:145], v[224:227], v[78:81]
	v_mfma_f32_16x16x32_bf16 v[70:73], v[176:179], v[224:227], 0
	v_mfma_f32_16x16x32_bf16 v[70:73], v[180:183], v[228:231], v[70:73]
	v_mfma_f32_16x16x32_bf16 v[66:69], v[188:191], v[228:231], 0
	v_mfma_f32_16x16x32_bf16 v[66:69], v[184:187], v[224:227], v[66:69]
	v_mfma_f32_16x16x32_bf16 v[82:85], v[184:187], v[216:219], 0
	v_mfma_f32_16x16x32_bf16 v[82:85], v[188:191], v[220:223], v[82:85]
	v_mfma_f32_16x16x32_bf16 v[86:89], v[180:183], v[220:223], 0
	v_mfma_f32_16x16x32_bf16 v[86:89], v[176:179], v[216:219], v[86:89]
	v_mfma_f32_16x16x32_bf16 v[102:105], v[176:179], v[208:211], 0
	v_mfma_f32_16x16x32_bf16 v[102:105], v[180:183], v[212:215], v[102:105]
	v_mfma_f32_16x16x32_bf16 v[98:101], v[188:191], v[212:215], 0
	v_mfma_f32_16x16x32_bf16 v[98:101], v[184:187], v[208:211], v[98:101]
	v_mfma_f32_16x16x32_bf16 v[114:117], v[184:187], v[192:195], 0
	v_mfma_f32_16x16x32_bf16 v[114:117], v[188:191], v[204:207], v[114:117]
	v_mfma_f32_16x16x32_bf16 v[118:121], v[180:183], v[204:207], 0
	v_mfma_f32_16x16x32_bf16 v[118:121], v[176:179], v[192:195], v[118:121]
	s_barrier
	s_mov_b32 m0, s42
	s_add_u32 s60, s22, 0x100000
	global_load_lds_dwordx4 v132, s[22:23]
	s_mov_b32 m0, s43
	s_addc_u32 s61, s23, 0
	global_load_lds_dwordx4 v136, s[22:23]
	s_mov_b32 m0, s44
	ds_read_b128 v[192:195], v150 offset:16384
	global_load_lds_dwordx4 v132, s[60:61]
	s_mov_b32 m0, s45
	ds_read_b128 v[204:207], v150 offset:17408
	global_load_lds_dwordx4 v136, s[60:61]
	ds_read_b128 v[208:211], v150 offset:18432
	ds_read_b128 v[212:215], v150 offset:19456
	ds_read_b128 v[216:219], v150 offset:20480
	ds_read_b128 v[220:223], v150 offset:21504
	ds_read_b128 v[224:227], v150 offset:22528
	ds_read_b128 v[228:231], v150 offset:23552
	s_waitcnt vmcnt(6)
	s_waitcnt lgkmcnt(0)
	s_barrier
	v_mfma_f32_16x16x32_bf16 v[62:65], v[142:145], v[192:195], 0
	v_mfma_f32_16x16x32_bf16 v[62:65], v[154:157], v[204:207], v[62:65]
	v_mfma_f32_16x16x32_bf16 v[58:61], v[168:171], v[204:207], 0
	v_mfma_f32_16x16x32_bf16 v[58:61], v[158:161], v[192:195], v[58:61]
	v_mfma_f32_16x16x32_bf16 v[42:45], v[158:161], v[208:211], 0
	v_mfma_f32_16x16x32_bf16 v[42:45], v[168:171], v[212:215], v[42:45]
	v_mfma_f32_16x16x32_bf16 v[46:49], v[154:157], v[212:215], 0
	v_mfma_f32_16x16x32_bf16 v[46:49], v[142:145], v[208:211], v[46:49]
	v_mfma_f32_16x16x32_bf16 v[30:33], v[142:145], v[216:219], 0
	v_mfma_f32_16x16x32_bf16 v[30:33], v[154:157], v[220:223], v[30:33]
	v_mfma_f32_16x16x32_bf16 v[26:29], v[168:171], v[220:223], 0
	v_mfma_f32_16x16x32_bf16 v[26:29], v[158:161], v[216:219], v[26:29]
	v_mfma_f32_16x16x32_bf16 v[10:13], v[158:161], v[224:227], 0
	v_mfma_f32_16x16x32_bf16 v[10:13], v[168:171], v[228:231], v[10:13]
	v_mfma_f32_16x16x32_bf16 v[14:17], v[154:157], v[228:231], 0
	v_mfma_f32_16x16x32_bf16 v[14:17], v[142:145], v[224:227], v[14:17]
	v_mfma_f32_16x16x32_bf16 v[6:9], v[176:179], v[224:227], 0
	v_mfma_f32_16x16x32_bf16 v[6:9], v[180:183], v[228:231], v[6:9]
	v_mfma_f32_16x16x32_bf16 v[2:5], v[188:191], v[228:231], 0
	v_mfma_f32_16x16x32_bf16 v[2:5], v[184:187], v[224:227], v[2:5]
	v_mfma_f32_16x16x32_bf16 v[18:21], v[184:187], v[216:219], 0
	v_mfma_f32_16x16x32_bf16 v[18:21], v[188:191], v[220:223], v[18:21]
	v_mfma_f32_16x16x32_bf16 v[22:25], v[180:183], v[220:223], 0
	v_mfma_f32_16x16x32_bf16 v[22:25], v[176:179], v[216:219], v[22:25]
	v_mfma_f32_16x16x32_bf16 v[38:41], v[176:179], v[208:211], 0
	v_mfma_f32_16x16x32_bf16 v[38:41], v[180:183], v[212:215], v[38:41]
	v_mfma_f32_16x16x32_bf16 v[34:37], v[188:191], v[212:215], 0
	v_mfma_f32_16x16x32_bf16 v[34:37], v[184:187], v[208:211], v[34:37]
	v_mfma_f32_16x16x32_bf16 v[50:53], v[184:187], v[192:195], 0
	v_mfma_f32_16x16x32_bf16 v[50:53], v[188:191], v[204:207], v[50:53]
	v_mfma_f32_16x16x32_bf16 v[54:57], v[180:183], v[204:207], 0
	v_mfma_f32_16x16x32_bf16 v[54:57], v[176:179], v[192:195], v[54:57]
	s_barrier
	s_mov_b32 m0, s29
	ds_read_b128 v[142:145], v151
	global_load_lds_dwordx4 v130, s[24:25]
	s_mov_b32 m0, s30
	ds_read_b128 v[154:157], v151 offset:1024
	global_load_lds_dwordx4 v134, s[24:25]
	s_add_u32 s24, s24, 0x100000
	s_addc_u32 s25, s25, 0
	s_mov_b32 m0, s31
	ds_read_b128 v[158:161], v151 offset:2048
	global_load_lds_dwordx4 v130, s[24:25]
	s_mov_b32 m0, s33
	ds_read_b128 v[168:171], v151 offset:3072
	global_load_lds_dwordx4 v134, s[24:25]
	ds_read_b128 v[176:179], v152
	ds_read_b128 v[180:183], v152 offset:1024
	ds_read_b128 v[184:187], v152 offset:2048
	ds_read_b128 v[188:191], v152 offset:3072
	ds_read_b128 v[192:195], v150 offset:32768
	ds_read_b128 v[204:207], v150 offset:33792
	ds_read_b128 v[208:211], v150 offset:34816
	ds_read_b128 v[212:215], v150 offset:35840
	ds_read_b128 v[216:219], v150 offset:36864
	ds_read_b128 v[220:223], v150 offset:37888
	ds_read_b128 v[224:227], v150 offset:38912
	ds_read_b128 v[228:231], v150 offset:39936
	s_waitcnt vmcnt(8)
	s_waitcnt lgkmcnt(0)
	s_barrier
	v_mfma_f32_16x16x32_bf16 v[126:129], v[142:145], v[192:195], v[126:129]
	v_mfma_f32_16x16x32_bf16 v[126:129], v[154:157], v[204:207], v[126:129]
	v_mfma_f32_16x16x32_bf16 v[122:125], v[168:171], v[204:207], v[122:125]
	v_mfma_f32_16x16x32_bf16 v[122:125], v[158:161], v[192:195], v[122:125]
	v_mfma_f32_16x16x32_bf16 v[106:109], v[158:161], v[208:211], v[106:109]
	v_mfma_f32_16x16x32_bf16 v[106:109], v[168:171], v[212:215], v[106:109]
	v_mfma_f32_16x16x32_bf16 v[110:113], v[154:157], v[212:215], v[110:113]
	v_mfma_f32_16x16x32_bf16 v[110:113], v[142:145], v[208:211], v[110:113]
	v_mfma_f32_16x16x32_bf16 v[94:97], v[142:145], v[216:219], v[94:97]
	v_mfma_f32_16x16x32_bf16 v[94:97], v[154:157], v[220:223], v[94:97]
	v_mfma_f32_16x16x32_bf16 v[90:93], v[168:171], v[220:223], v[90:93]
	v_mfma_f32_16x16x32_bf16 v[90:93], v[158:161], v[216:219], v[90:93]
	v_mfma_f32_16x16x32_bf16 v[74:77], v[158:161], v[224:227], v[74:77]
	v_mfma_f32_16x16x32_bf16 v[74:77], v[168:171], v[228:231], v[74:77]
	v_mfma_f32_16x16x32_bf16 v[78:81], v[154:157], v[228:231], v[78:81]
	v_mfma_f32_16x16x32_bf16 v[78:81], v[142:145], v[224:227], v[78:81]
	v_mfma_f32_16x16x32_bf16 v[70:73], v[176:179], v[224:227], v[70:73]
	v_mfma_f32_16x16x32_bf16 v[70:73], v[180:183], v[228:231], v[70:73]
	v_mfma_f32_16x16x32_bf16 v[66:69], v[188:191], v[228:231], v[66:69]
	v_mfma_f32_16x16x32_bf16 v[66:69], v[184:187], v[224:227], v[66:69]
	v_mfma_f32_16x16x32_bf16 v[82:85], v[184:187], v[216:219], v[82:85]
	v_mfma_f32_16x16x32_bf16 v[82:85], v[188:191], v[220:223], v[82:85]
	v_mfma_f32_16x16x32_bf16 v[86:89], v[180:183], v[220:223], v[86:89]
	v_mfma_f32_16x16x32_bf16 v[86:89], v[176:179], v[216:219], v[86:89]
	v_mfma_f32_16x16x32_bf16 v[102:105], v[176:179], v[208:211], v[102:105]
	v_mfma_f32_16x16x32_bf16 v[102:105], v[180:183], v[212:215], v[102:105]
	v_mfma_f32_16x16x32_bf16 v[98:101], v[188:191], v[212:215], v[98:101]
	v_mfma_f32_16x16x32_bf16 v[98:101], v[184:187], v[208:211], v[98:101]
	v_mfma_f32_16x16x32_bf16 v[114:117], v[184:187], v[192:195], v[114:117]
	v_mfma_f32_16x16x32_bf16 v[114:117], v[188:191], v[204:207], v[114:117]
	v_mfma_f32_16x16x32_bf16 v[118:121], v[180:183], v[204:207], v[118:121]
	v_mfma_f32_16x16x32_bf16 v[118:121], v[176:179], v[192:195], v[118:121]
	s_barrier
	s_mov_b32 m0, s46
	s_add_u32 s22, s22, 0x80
	s_addc_u32 s23, s23, 0
	global_load_lds_dwordx4 v132, s[22:23]
	s_mov_b32 m0, s47
	ds_read_b128 v[192:195], v150 offset:49152
	global_load_lds_dwordx4 v136, s[22:23]
	s_mov_b32 m0, s48
	s_add_u32 s22, s22, 0x100000
	s_addc_u32 s23, s23, 0
	global_load_lds_dwordx4 v132, s[22:23]
	s_mov_b32 m0, s49
	ds_read_b128 v[204:207], v150 offset:50176
	global_load_lds_dwordx4 v136, s[22:23]
	ds_read_b128 v[208:211], v150 offset:51200
	ds_read_b128 v[212:215], v150 offset:52224
	ds_read_b128 v[216:219], v150 offset:53248
	ds_read_b128 v[220:223], v150 offset:54272
	ds_read_b128 v[224:227], v150 offset:55296
	ds_read_b128 v[228:231], v150 offset:56320
	s_waitcnt vmcnt(6)
	s_waitcnt lgkmcnt(0)
	s_barrier
	v_mfma_f32_16x16x32_bf16 v[62:65], v[142:145], v[192:195], v[62:65]
	v_mfma_f32_16x16x32_bf16 v[62:65], v[154:157], v[204:207], v[62:65]
	v_mfma_f32_16x16x32_bf16 v[58:61], v[168:171], v[204:207], v[58:61]
	v_mfma_f32_16x16x32_bf16 v[58:61], v[158:161], v[192:195], v[58:61]
	v_mfma_f32_16x16x32_bf16 v[42:45], v[158:161], v[208:211], v[42:45]
	v_mfma_f32_16x16x32_bf16 v[42:45], v[168:171], v[212:215], v[42:45]
	v_mfma_f32_16x16x32_bf16 v[46:49], v[154:157], v[212:215], v[46:49]
	v_mfma_f32_16x16x32_bf16 v[46:49], v[142:145], v[208:211], v[46:49]
	v_mfma_f32_16x16x32_bf16 v[30:33], v[142:145], v[216:219], v[30:33]
	v_mfma_f32_16x16x32_bf16 v[30:33], v[154:157], v[220:223], v[30:33]
	v_mfma_f32_16x16x32_bf16 v[26:29], v[168:171], v[220:223], v[26:29]
	v_mfma_f32_16x16x32_bf16 v[26:29], v[158:161], v[216:219], v[26:29]
	v_mfma_f32_16x16x32_bf16 v[10:13], v[158:161], v[224:227], v[10:13]
	v_mfma_f32_16x16x32_bf16 v[10:13], v[168:171], v[228:231], v[10:13]
	v_mfma_f32_16x16x32_bf16 v[14:17], v[154:157], v[228:231], v[14:17]
	v_mfma_f32_16x16x32_bf16 v[14:17], v[142:145], v[224:227], v[14:17]
	v_mfma_f32_16x16x32_bf16 v[6:9], v[176:179], v[224:227], v[6:9]
	v_mfma_f32_16x16x32_bf16 v[6:9], v[180:183], v[228:231], v[6:9]
	v_mfma_f32_16x16x32_bf16 v[2:5], v[188:191], v[228:231], v[2:5]
	v_mfma_f32_16x16x32_bf16 v[2:5], v[184:187], v[224:227], v[2:5]
	v_mfma_f32_16x16x32_bf16 v[18:21], v[184:187], v[216:219], v[18:21]
	v_mfma_f32_16x16x32_bf16 v[18:21], v[188:191], v[220:223], v[18:21]
	v_mfma_f32_16x16x32_bf16 v[22:25], v[180:183], v[220:223], v[22:25]
	v_mfma_f32_16x16x32_bf16 v[22:25], v[176:179], v[216:219], v[22:25]
	v_mfma_f32_16x16x32_bf16 v[38:41], v[176:179], v[208:211], v[38:41]
	v_mfma_f32_16x16x32_bf16 v[38:41], v[180:183], v[212:215], v[38:41]
	v_mfma_f32_16x16x32_bf16 v[34:37], v[188:191], v[212:215], v[34:37]
	v_mfma_f32_16x16x32_bf16 v[34:37], v[184:187], v[208:211], v[34:37]
	v_mfma_f32_16x16x32_bf16 v[50:53], v[184:187], v[192:195], v[50:53]
	v_mfma_f32_16x16x32_bf16 v[50:53], v[188:191], v[204:207], v[50:53]
	v_mfma_f32_16x16x32_bf16 v[54:57], v[180:183], v[204:207], v[54:57]
	v_mfma_f32_16x16x32_bf16 v[54:57], v[176:179], v[192:195], v[54:57]
	s_barrier
	s_add_i32 s57, s57, 2
	s_add_u32 s20, s20, 0x100
	s_addc_u32 s21, s21, 0
	s_add_u32 s55, s55, 0x100
	s_addc_u32 s56, s56, 0

.LBB0_2617:
	s_and_b64 s[24:25], s[24:25], exec
	s_cselect_b32 s25, s7, s29
	s_cselect_b32 s24, s6, s28
	s_add_u32 s28, s28, 0x2b0080
	s_addc_u32 s29, s29, 0
	s_add_u32 s60, s30, 0x100
	s_addc_u32 s61, s31, 0
	s_mov_b32 s62, -2
	s_waitcnt lgkmcnt(0)
	s_add_u32 s64, s28, 0xffd50000
	s_addc_u32 s65, s29, -1
	s_mov_b32 m0, s44
	ds_read_b128 v[142:145], v156
	global_load_lds_dwordx4 v130, s[64:65]
	s_mov_b32 m0, s45
	ds_read_b128 v[168:171], v156 offset:1024
	global_load_lds_dwordx4 v134, s[64:65]
	s_mov_b32 m0, s46
	ds_read_b128 v[172:175], v156 offset:2048
	global_load_lds_dwordx4 v138, s[28:29]
	s_mov_b32 m0, s47
	ds_read_b128 v[176:179], v156 offset:3072
	global_load_lds_dwordx4 v140, s[28:29]
	ds_read_b128 v[180:183], v157
	ds_read_b128 v[184:187], v157 offset:1024
	ds_read_b128 v[188:191], v157 offset:2048
	ds_read_b128 v[192:195], v157 offset:3072
	s_add_u32 s30, s28, 0xffd50080
	s_addc_u32 s31, s29, -1
	s_cmpk_eq_i32 s62, 0xa8
	s_cselect_b32 s35, s25, s31
	s_cselect_b32 s34, s24, s30
	s_cselect_b32 s31, s23, s61
	s_cselect_b32 s30, s22, s60
	ds_read_b128 v[196:199], v158
	ds_read_b128 v[200:203], v158 offset:1024
	ds_read_b128 v[204:207], v158 offset:2048
	ds_read_b128 v[208:211], v158 offset:3072
	ds_read_b128 v[212:215], v158 offset:4096
	ds_read_b128 v[216:219], v158 offset:5120
	ds_read_b128 v[220:223], v158 offset:6144
	ds_read_b128 v[224:227], v158 offset:7168
	s_waitcnt vmcnt(8)
	s_waitcnt lgkmcnt(0)
	s_barrier
	v_mfma_f32_16x16x32_bf16 v[126:129], v[142:145], v[196:199], 0
	v_mfma_f32_16x16x32_bf16 v[126:129], v[168:171], v[200:203], v[126:129]
	v_mfma_f32_16x16x32_bf16 v[122:125], v[176:179], v[200:203], 0
	v_mfma_f32_16x16x32_bf16 v[122:125], v[172:175], v[196:199], v[122:125]
	v_mfma_f32_16x16x32_bf16 v[106:109], v[172:175], v[204:207], 0
	v_mfma_f32_16x16x32_bf16 v[106:109], v[176:179], v[208:211], v[106:109]
	v_mfma_f32_16x16x32_bf16 v[110:113], v[168:171], v[208:211], 0
	v_mfma_f32_16x16x32_bf16 v[110:113], v[142:145], v[204:207], v[110:113]
	v_mfma_f32_16x16x32_bf16 v[94:97], v[142:145], v[212:215], 0
	v_mfma_f32_16x16x32_bf16 v[94:97], v[168:171], v[216:219], v[94:97]
	v_mfma_f32_16x16x32_bf16 v[90:93], v[176:179], v[216:219], 0
	v_mfma_f32_16x16x32_bf16 v[90:93], v[172:175], v[212:215], v[90:93]
	v_mfma_f32_16x16x32_bf16 v[74:77], v[172:175], v[220:223], 0
	v_mfma_f32_16x16x32_bf16 v[74:77], v[176:179], v[224:227], v[74:77]
	v_mfma_f32_16x16x32_bf16 v[78:81], v[168:171], v[224:227], 0
	v_mfma_f32_16x16x32_bf16 v[78:81], v[142:145], v[220:223], v[78:81]
	v_mfma_f32_16x16x32_bf16 v[70:73], v[180:183], v[220:223], 0
	v_mfma_f32_16x16x32_bf16 v[70:73], v[184:187], v[224:227], v[70:73]
	v_mfma_f32_16x16x32_bf16 v[66:69], v[192:195], v[224:227], 0
	v_mfma_f32_16x16x32_bf16 v[66:69], v[188:191], v[220:223], v[66:69]
	v_mfma_f32_16x16x32_bf16 v[82:85], v[188:191], v[212:215], 0
	v_mfma_f32_16x16x32_bf16 v[82:85], v[192:195], v[216:219], v[82:85]
	v_mfma_f32_16x16x32_bf16 v[86:89], v[184:187], v[216:219], 0
	v_mfma_f32_16x16x32_bf16 v[86:89], v[180:183], v[212:215], v[86:89]
	v_mfma_f32_16x16x32_bf16 v[102:105], v[180:183], v[204:207], 0
	v_mfma_f32_16x16x32_bf16 v[102:105], v[184:187], v[208:211], v[102:105]
	v_mfma_f32_16x16x32_bf16 v[98:101], v[192:195], v[208:211], 0
	v_mfma_f32_16x16x32_bf16 v[98:101], v[188:191], v[204:207], v[98:101]
	v_mfma_f32_16x16x32_bf16 v[114:117], v[188:191], v[196:199], 0
	v_mfma_f32_16x16x32_bf16 v[114:117], v[192:195], v[200:203], v[114:117]
	v_mfma_f32_16x16x32_bf16 v[118:121], v[184:187], v[200:203], 0
	v_mfma_f32_16x16x32_bf16 v[118:121], v[180:183], v[196:199], v[118:121]
	s_barrier
	s_mov_b32 m0, s48
	s_add_u32 s64, s30, 0x2b0000
	global_load_lds_dwordx4 v132, s[30:31]
	s_mov_b32 m0, s49
	s_addc_u32 s65, s31, 0
	global_load_lds_dwordx4 v136, s[30:31]
	s_mov_b32 m0, s50
	ds_read_b128 v[196:199], v158 offset:16384
	global_load_lds_dwordx4 v132, s[64:65]
	s_mov_b32 m0, s51
	ds_read_b128 v[200:203], v158 offset:17408
	global_load_lds_dwordx4 v136, s[64:65]
	ds_read_b128 v[204:207], v158 offset:18432
	ds_read_b128 v[208:211], v158 offset:19456
	ds_read_b128 v[212:215], v158 offset:20480
	ds_read_b128 v[216:219], v158 offset:21504
	ds_read_b128 v[220:223], v158 offset:22528
	ds_read_b128 v[224:227], v158 offset:23552
	s_waitcnt vmcnt(6)
	s_waitcnt lgkmcnt(0)
	s_barrier
	v_mfma_f32_16x16x32_bf16 v[62:65], v[142:145], v[196:199], 0
	v_mfma_f32_16x16x32_bf16 v[62:65], v[168:171], v[200:203], v[62:65]
	v_mfma_f32_16x16x32_bf16 v[58:61], v[176:179], v[200:203], 0
	v_mfma_f32_16x16x32_bf16 v[58:61], v[172:175], v[196:199], v[58:61]
	v_mfma_f32_16x16x32_bf16 v[42:45], v[172:175], v[204:207], 0
	v_mfma_f32_16x16x32_bf16 v[42:45], v[176:179], v[208:211], v[42:45]
	v_mfma_f32_16x16x32_bf16 v[46:49], v[168:171], v[208:211], 0
	v_mfma_f32_16x16x32_bf16 v[46:49], v[142:145], v[204:207], v[46:49]
	v_mfma_f32_16x16x32_bf16 v[30:33], v[142:145], v[212:215], 0
	v_mfma_f32_16x16x32_bf16 v[30:33], v[168:171], v[216:219], v[30:33]
	v_mfma_f32_16x16x32_bf16 v[26:29], v[176:179], v[216:219], 0
	v_mfma_f32_16x16x32_bf16 v[26:29], v[172:175], v[212:215], v[26:29]
	v_mfma_f32_16x16x32_bf16 v[10:13], v[172:175], v[220:223], 0
	v_mfma_f32_16x16x32_bf16 v[10:13], v[176:179], v[224:227], v[10:13]
	v_mfma_f32_16x16x32_bf16 v[14:17], v[168:171], v[224:227], 0
	v_mfma_f32_16x16x32_bf16 v[14:17], v[142:145], v[220:223], v[14:17]
	v_mfma_f32_16x16x32_bf16 v[6:9], v[180:183], v[220:223], 0
	v_mfma_f32_16x16x32_bf16 v[6:9], v[184:187], v[224:227], v[6:9]
	v_mfma_f32_16x16x32_bf16 v[2:5], v[192:195], v[224:227], 0
	v_mfma_f32_16x16x32_bf16 v[2:5], v[188:191], v[220:223], v[2:5]
	v_mfma_f32_16x16x32_bf16 v[18:21], v[188:191], v[212:215], 0
	v_mfma_f32_16x16x32_bf16 v[18:21], v[192:195], v[216:219], v[18:21]
	v_mfma_f32_16x16x32_bf16 v[22:25], v[184:187], v[216:219], 0
	v_mfma_f32_16x16x32_bf16 v[22:25], v[180:183], v[212:215], v[22:25]
	v_mfma_f32_16x16x32_bf16 v[38:41], v[180:183], v[204:207], 0
	v_mfma_f32_16x16x32_bf16 v[38:41], v[184:187], v[208:211], v[38:41]
	v_mfma_f32_16x16x32_bf16 v[34:37], v[192:195], v[208:211], 0
	v_mfma_f32_16x16x32_bf16 v[34:37], v[188:191], v[204:207], v[34:37]
	v_mfma_f32_16x16x32_bf16 v[50:53], v[188:191], v[196:199], 0
	v_mfma_f32_16x16x32_bf16 v[50:53], v[192:195], v[200:203], v[50:53]
	v_mfma_f32_16x16x32_bf16 v[54:57], v[184:187], v[200:203], 0
	v_mfma_f32_16x16x32_bf16 v[54:57], v[180:183], v[196:199], v[54:57]
	s_barrier
	s_mov_b32 m0, s39
	ds_read_b128 v[142:145], v159
	global_load_lds_dwordx4 v130, s[34:35]
	s_mov_b32 m0, s40
	ds_read_b128 v[168:171], v159 offset:1024
	global_load_lds_dwordx4 v134, s[34:35]
	s_add_u32 s34, s34, 0x2b0000
	s_addc_u32 s35, s35, 0
	s_mov_b32 m0, s41
	ds_read_b128 v[172:175], v159 offset:2048
	global_load_lds_dwordx4 v130, s[34:35]
	s_mov_b32 m0, s42
	ds_read_b128 v[176:179], v159 offset:3072
	global_load_lds_dwordx4 v134, s[34:35]
	ds_read_b128 v[180:183], v160
	ds_read_b128 v[184:187], v160 offset:1024
	ds_read_b128 v[188:191], v160 offset:2048
	ds_read_b128 v[192:195], v160 offset:3072
	ds_read_b128 v[196:199], v158 offset:32768
	ds_read_b128 v[200:203], v158 offset:33792
	ds_read_b128 v[204:207], v158 offset:34816
	ds_read_b128 v[208:211], v158 offset:35840
	ds_read_b128 v[212:215], v158 offset:36864
	ds_read_b128 v[216:219], v158 offset:37888
	ds_read_b128 v[220:223], v158 offset:38912
	ds_read_b128 v[224:227], v158 offset:39936
	s_waitcnt vmcnt(8)
	s_waitcnt lgkmcnt(0)
	s_barrier
	v_mfma_f32_16x16x32_bf16 v[126:129], v[142:145], v[196:199], v[126:129]
	v_mfma_f32_16x16x32_bf16 v[126:129], v[168:171], v[200:203], v[126:129]
	v_mfma_f32_16x16x32_bf16 v[122:125], v[176:179], v[200:203], v[122:125]
	v_mfma_f32_16x16x32_bf16 v[122:125], v[172:175], v[196:199], v[122:125]
	v_mfma_f32_16x16x32_bf16 v[106:109], v[172:175], v[204:207], v[106:109]
	v_mfma_f32_16x16x32_bf16 v[106:109], v[176:179], v[208:211], v[106:109]
	v_mfma_f32_16x16x32_bf16 v[110:113], v[168:171], v[208:211], v[110:113]
	v_mfma_f32_16x16x32_bf16 v[110:113], v[142:145], v[204:207], v[110:113]
	v_mfma_f32_16x16x32_bf16 v[94:97], v[142:145], v[212:215], v[94:97]
	v_mfma_f32_16x16x32_bf16 v[94:97], v[168:171], v[216:219], v[94:97]
	v_mfma_f32_16x16x32_bf16 v[90:93], v[176:179], v[216:219], v[90:93]
	v_mfma_f32_16x16x32_bf16 v[90:93], v[172:175], v[212:215], v[90:93]
	v_mfma_f32_16x16x32_bf16 v[74:77], v[172:175], v[220:223], v[74:77]
	v_mfma_f32_16x16x32_bf16 v[74:77], v[176:179], v[224:227], v[74:77]
	v_mfma_f32_16x16x32_bf16 v[78:81], v[168:171], v[224:227], v[78:81]
	v_mfma_f32_16x16x32_bf16 v[78:81], v[142:145], v[220:223], v[78:81]
	v_mfma_f32_16x16x32_bf16 v[70:73], v[180:183], v[220:223], v[70:73]
	v_mfma_f32_16x16x32_bf16 v[70:73], v[184:187], v[224:227], v[70:73]
	v_mfma_f32_16x16x32_bf16 v[66:69], v[192:195], v[224:227], v[66:69]
	v_mfma_f32_16x16x32_bf16 v[66:69], v[188:191], v[220:223], v[66:69]
	v_mfma_f32_16x16x32_bf16 v[82:85], v[188:191], v[212:215], v[82:85]
	v_mfma_f32_16x16x32_bf16 v[82:85], v[192:195], v[216:219], v[82:85]
	v_mfma_f32_16x16x32_bf16 v[86:89], v[184:187], v[216:219], v[86:89]
	v_mfma_f32_16x16x32_bf16 v[86:89], v[180:183], v[212:215], v[86:89]
	v_mfma_f32_16x16x32_bf16 v[102:105], v[180:183], v[204:207], v[102:105]
	v_mfma_f32_16x16x32_bf16 v[102:105], v[184:187], v[208:211], v[102:105]
	v_mfma_f32_16x16x32_bf16 v[98:101], v[192:195], v[208:211], v[98:101]
	v_mfma_f32_16x16x32_bf16 v[98:101], v[188:191], v[204:207], v[98:101]
	v_mfma_f32_16x16x32_bf16 v[114:117], v[188:191], v[196:199], v[114:117]
	v_mfma_f32_16x16x32_bf16 v[114:117], v[192:195], v[200:203], v[114:117]
	v_mfma_f32_16x16x32_bf16 v[118:121], v[184:187], v[200:203], v[118:121]
	v_mfma_f32_16x16x32_bf16 v[118:121], v[180:183], v[196:199], v[118:121]
	s_barrier
	s_mov_b32 m0, s52
	s_add_u32 s30, s30, 0x80
	s_addc_u32 s31, s31, 0
	global_load_lds_dwordx4 v132, s[30:31]
	s_mov_b32 m0, s53
	ds_read_b128 v[196:199], v158 offset:49152
	global_load_lds_dwordx4 v136, s[30:31]
	s_mov_b32 m0, s54
	s_add_u32 s30, s30, 0x2b0000
	s_addc_u32 s31, s31, 0
	global_load_lds_dwordx4 v132, s[30:31]
	s_mov_b32 m0, s55
	ds_read_b128 v[200:203], v158 offset:50176
	global_load_lds_dwordx4 v136, s[30:31]
	ds_read_b128 v[204:207], v158 offset:51200
	ds_read_b128 v[208:211], v158 offset:52224
	ds_read_b128 v[212:215], v158 offset:53248
	ds_read_b128 v[216:219], v158 offset:54272
	ds_read_b128 v[220:223], v158 offset:55296
	ds_read_b128 v[224:227], v158 offset:56320
	s_waitcnt vmcnt(6)
	s_waitcnt lgkmcnt(0)
	s_barrier
	v_mfma_f32_16x16x32_bf16 v[62:65], v[142:145], v[196:199], v[62:65]
	v_mfma_f32_16x16x32_bf16 v[62:65], v[168:171], v[200:203], v[62:65]
	v_mfma_f32_16x16x32_bf16 v[58:61], v[176:179], v[200:203], v[58:61]
	v_mfma_f32_16x16x32_bf16 v[58:61], v[172:175], v[196:199], v[58:61]
	v_mfma_f32_16x16x32_bf16 v[42:45], v[172:175], v[204:207], v[42:45]
	v_mfma_f32_16x16x32_bf16 v[42:45], v[176:179], v[208:211], v[42:45]
	v_mfma_f32_16x16x32_bf16 v[46:49], v[168:171], v[208:211], v[46:49]
	v_mfma_f32_16x16x32_bf16 v[46:49], v[142:145], v[204:207], v[46:49]
	v_mfma_f32_16x16x32_bf16 v[30:33], v[142:145], v[212:215], v[30:33]
	v_mfma_f32_16x16x32_bf16 v[30:33], v[168:171], v[216:219], v[30:33]
	v_mfma_f32_16x16x32_bf16 v[26:29], v[176:179], v[216:219], v[26:29]
	v_mfma_f32_16x16x32_bf16 v[26:29], v[172:175], v[212:215], v[26:29]
	v_mfma_f32_16x16x32_bf16 v[10:13], v[172:175], v[220:223], v[10:13]
	v_mfma_f32_16x16x32_bf16 v[10:13], v[176:179], v[224:227], v[10:13]
	v_mfma_f32_16x16x32_bf16 v[14:17], v[168:171], v[224:227], v[14:17]
	v_mfma_f32_16x16x32_bf16 v[14:17], v[142:145], v[220:223], v[14:17]
	v_mfma_f32_16x16x32_bf16 v[6:9], v[180:183], v[220:223], v[6:9]
	v_mfma_f32_16x16x32_bf16 v[6:9], v[184:187], v[224:227], v[6:9]
	v_mfma_f32_16x16x32_bf16 v[2:5], v[192:195], v[224:227], v[2:5]
	v_mfma_f32_16x16x32_bf16 v[2:5], v[188:191], v[220:223], v[2:5]
	v_mfma_f32_16x16x32_bf16 v[18:21], v[188:191], v[212:215], v[18:21]
	v_mfma_f32_16x16x32_bf16 v[18:21], v[192:195], v[216:219], v[18:21]
	v_mfma_f32_16x16x32_bf16 v[22:25], v[184:187], v[216:219], v[22:25]
	v_mfma_f32_16x16x32_bf16 v[22:25], v[180:183], v[212:215], v[22:25]
	v_mfma_f32_16x16x32_bf16 v[38:41], v[180:183], v[204:207], v[38:41]
	v_mfma_f32_16x16x32_bf16 v[38:41], v[184:187], v[208:211], v[38:41]
	v_mfma_f32_16x16x32_bf16 v[34:37], v[192:195], v[208:211], v[34:37]
	v_mfma_f32_16x16x32_bf16 v[34:37], v[188:191], v[204:207], v[34:37]
	v_mfma_f32_16x16x32_bf16 v[50:53], v[188:191], v[196:199], v[50:53]
	v_mfma_f32_16x16x32_bf16 v[50:53], v[192:195], v[200:203], v[50:53]
	v_mfma_f32_16x16x32_bf16 v[54:57], v[184:187], v[200:203], v[54:57]
	v_mfma_f32_16x16x32_bf16 v[54:57], v[180:183], v[196:199], v[54:57]
	s_barrier
	s_add_i32 s62, s62, 2
	s_add_u32 s28, s28, 0x100
	s_addc_u32 s29, s29, 0
	s_add_u32 s60, s60, 0x100
	s_addc_u32 s61, s61, 0
